# GEMM epilogue cross-lane sums (xor 16 / xor 32) through permlane swaps instead of LDS bpermute round trips (41 sites)
# speedup vs baseline: 1.0044x; 1.0044x over previous
; __device__ __forceinline__ unsigned cvt_pk_bf16(float lo, float hi) { f32x2 v = {lo, hi}; return __builtin_bit_cast(unsigned, __builtin_convertvector(v, bf2_t)); }
;     __device__ __forceinline__ void operator()(const f32x4 (&acc)[2][2][4][2], const Unit& u, int wr, int wc, int fr, int fq) const {
;     ...
;                 for (int bj = 0; bj < 2; ++bj) raw[m][bj] = *(const u32x4*)(base16 + (size_t)(row0 + ai * HALF + m * 16) * 2048 + col0 + bj * HALF);
; #pragma unroll
;             for (int m = 0; m < 4; ++m) {
;                 const int row = row0 + ai * HALF + m * 16;
;                 const size_t off = (size_t)row * 2048 + col0;
;                 float sq = 0.f;
; #pragma unroll
;                 for (int bj = 0; bj < 2; ++bj) {
;                     const u32x4 w = raw[m][bj];
;                     const f32x4 r0 = {__uint_as_float(w.x << 16), __uint_as_float(w.x & 0xffff0000u), __uint_as_float(w.y << 16), __uint_as_float(w.y & 0xffff0000u)};
;                     const f32x4 r1 = {__uint_as_float(w.z << 16), __uint_as_float(w.z & 0xffff0000u), __uint_as_float(w.w << 16), __uint_as_float(w.w & 0xffff0000u)};
;                     const f32x4 v0 = r0 + acc[ai][bj][m][0], v1 = r1 + acc[ai][bj][m][1];
;                     if (out32) { *(f32x4*)(out32 + off + bj * HALF) = v0; *(f32x4*)(out32 + off + bj * HALF + 4) = v1; }
;                     if (XB) { u32x4 o; o.x = cvt_pk_bf16(v0[0], v0[1]); o.y = cvt_pk_bf16(v0[2], v0[3]); o.z = cvt_pk_bf16(v1[0], v1[1]); o.w = cvt_pk_bf16(v1[2], v1[3]);
;                               *(u32x4*)(XB + off + bj * HALF) = o;
;                               sq += ((v0[0] * v0[0] + v0[1] * v0[1]) + (v0[2] * v0[2] + v0[3] * v0[3])) + ((v1[0] * v1[0] + v1[1] * v1[1]) + (v1[2] * v1[2] + v1[3] * v1[3])); }
;                 }
;                 if (XB) { sq += __shfl_xor(sq, 16); sq += __shfl_xor(sq, 32); if (fq == 0) SS[(size_t)row * 32 + u.pn * 4 + wc] = sq; }
.LBB0_310:
	v_lshl_or_b32 v128, s6, 8, v180
	v_lshl_add_u32 v170, s8, 8, v178
	v_ashrrev_i32_e32 v129, 31, v128
	s_lshl_b32 s26, s6, 2
	v_readlane_b32 s6, v254, 51
	v_lshlrev_b64 v[194:195], 1, v[128:129]
	v_readlane_b32 s7, v254, 52
	v_ashrrev_i32_e32 v171, 31, v170
	v_lshlrev_b64 v[198:199], 12, v[170:171]
	v_lshl_add_u64 v[168:169], s[6:7], 0, v[194:195]
	v_or_b32_e32 v176, 16, v170
	v_lshl_add_u64 v[128:129], v[168:169], 0, v[198:199]
	v_ashrrev_i32_e32 v177, 31, v176
	global_load_dwordx4 v[186:189], v[128:129], off
	global_load_dwordx4 v[190:193], v[128:129], off offset:256
	v_lshlrev_b64 v[128:129], 12, v[176:177]
	v_or_b32_e32 v174, 32, v170
	v_lshl_add_u64 v[128:129], v[168:169], 0, v[128:129]
	v_ashrrev_i32_e32 v175, 31, v174
	global_load_dwordx4 v[148:151], v[128:129], off
	global_load_dwordx4 v[144:147], v[128:129], off offset:256
	v_lshlrev_b64 v[128:129], 12, v[174:175]
	v_or_b32_e32 v172, 48, v170
	v_lshl_add_u64 v[128:129], v[168:169], 0, v[128:129]
	v_ashrrev_i32_e32 v173, 31, v172
	global_load_dwordx4 v[140:143], v[128:129], off
	global_load_dwordx4 v[136:139], v[128:129], off offset:256
	v_lshlrev_b64 v[128:129], 12, v[172:173]
	v_lshl_add_u64 v[128:129], v[168:169], 0, v[128:129]
	global_load_dwordx4 v[132:135], v[128:129], off
	s_nop 0
	global_load_dwordx4 v[128:131], v[128:129], off offset:256
	v_lshl_add_u64 v[198:199], s[6:7], 0, v[198:199]
	v_lshl_add_u64 v[194:195], v[198:199], 0, v[194:195]
	v_cndmask_b32_e64 v185, 0, 1, s[16:17]
	s_ashr_i32 s27, s26, 31
	v_cmp_ne_u32_e64 s[6:7], 1, v185
	s_andn2_b64 vcc, exec, s[16:17]
	v_add_u32_e32 v244, 0x80, v170
	v_ashrrev_i32_e32 v245, 31, v244
	v_lshlrev_b64 v[244:245], 12, v[244:245]
	v_lshl_add_u64 v[244:245], v[168:169], 0, v[244:245]
	global_load_dwordx4 v[206:209], v[244:245], off
	global_load_dwordx4 v[210:213], v[244:245], off offset:256
	v_add_u32_e32 v244, 0x90, v170
	v_ashrrev_i32_e32 v245, 31, v244
	v_lshlrev_b64 v[244:245], 12, v[244:245]
	v_lshl_add_u64 v[244:245], v[168:169], 0, v[244:245]
	global_load_dwordx4 v[214:217], v[244:245], off
	global_load_dwordx4 v[218:221], v[244:245], off offset:256
	v_add_u32_e32 v244, 0xa0, v170
	v_ashrrev_i32_e32 v245, 31, v244
	v_lshlrev_b64 v[244:245], 12, v[244:245]
	v_lshl_add_u64 v[244:245], v[168:169], 0, v[244:245]
	global_load_dwordx4 v[228:231], v[244:245], off
	global_load_dwordx4 v[232:235], v[244:245], off offset:256
	v_add_u32_e32 v244, 0xb0, v170
	v_ashrrev_i32_e32 v245, 31, v244
	v_lshlrev_b64 v[244:245], 12, v[244:245]
	v_lshl_add_u64 v[244:245], v[168:169], 0, v[244:245]
	global_load_dwordx4 v[236:239], v[244:245], off
	global_load_dwordx4 v[240:243], v[244:245], off offset:256
	s_waitcnt vmcnt(0)
	v_lshlrev_b32_e32 v200, 16, v186
	v_and_b32_e32 v201, 0xffff0000, v186
	v_lshlrev_b32_e32 v186, 16, v187
	v_and_b32_e32 v187, 0xffff0000, v187
	v_lshlrev_b32_e32 v202, 16, v188
	v_and_b32_e32 v203, 0xffff0000, v188
	v_lshlrev_b32_e32 v188, 16, v189
	v_and_b32_e32 v189, 0xffff0000, v189
	v_pk_add_f32 v[126:127], v[126:127], v[186:187]
	v_pk_add_f32 v[124:125], v[124:125], v[200:201]
	v_pk_add_f32 v[122:123], v[122:123], v[188:189]
	v_pk_add_f32 v[120:121], v[120:121], v[202:203]
	v_cvt_pk_bf16_f32 v186, v124, v125
	v_cvt_pk_bf16_f32 v187, v126, v127
	v_cvt_pk_bf16_f32 v188, v120, v121
	v_cvt_pk_bf16_f32 v189, v122, v123
	global_store_dwordx4 v[194:195], v[186:189], off
	s_nop 1
	v_lshlrev_b32_e32 v186, 16, v190
	v_and_b32_e32 v187, 0xffff0000, v190
	v_lshlrev_b32_e32 v188, 16, v191
	v_and_b32_e32 v189, 0xffff0000, v191
	v_lshlrev_b32_e32 v190, 16, v192
	v_and_b32_e32 v191, 0xffff0000, v192
	v_lshlrev_b32_e32 v192, 16, v193
	v_and_b32_e32 v193, 0xffff0000, v193
	v_pk_add_f32 v[118:119], v[118:119], v[188:189]
	v_pk_add_f32 v[116:117], v[116:117], v[186:187]
	v_pk_add_f32 v[114:115], v[114:115], v[192:193]
	v_pk_add_f32 v[112:113], v[112:113], v[190:191]
	v_cvt_pk_bf16_f32 v186, v116, v117
	v_cvt_pk_bf16_f32 v187, v118, v119
	v_cvt_pk_bf16_f32 v188, v112, v113
	v_cvt_pk_bf16_f32 v189, v114, v115
	global_store_dwordx4 v[194:195], v[186:189], off offset:256
	s_cbranch_vccnz .LBB0_314
	v_mul_f32_e32 v113, v113, v113
	v_mul_f32_e32 v125, v125, v125
	v_mul_f32_e32 v121, v121, v121
	v_mul_f32_e32 v117, v117, v117
	v_fmac_f32_e32 v113, v112, v112
	v_mul_f32_e32 v112, v115, v115
	v_fmac_f32_e32 v125, v124, v124
	v_mul_f32_e32 v124, v127, v127
	v_fmac_f32_e32 v121, v120, v120
	v_mul_f32_e32 v120, v123, v123
	v_fmac_f32_e32 v117, v116, v116
	v_mul_f32_e32 v116, v119, v119
	v_fmac_f32_e32 v112, v114, v114
	v_and_b32_e32 v114, 64, v184
	v_fmac_f32_e32 v124, v126, v126
	v_fmac_f32_e32 v120, v122, v122
	v_fmac_f32_e32 v116, v118, v118
	v_add_f32_e32 v112, v113, v112
	v_xor_b32_e32 v113, 16, v184
	v_add_u32_e32 v114, 64, v114
	v_add_f32_e32 v124, v125, v124
	v_add_f32_e32 v120, v121, v120
	v_add_f32_e32 v116, v117, v116
	v_cmp_lt_i32_e32 vcc, v113, v114
	v_add_f32_e32 v120, v124, v120
	v_add_f32_e32 v112, v116, v112
	v_cndmask_b32_e32 v113, v184, v113, vcc
	v_add_f32_e32 v112, v120, v112
	v_lshlrev_b32_e32 v113, 2, v113
	v_mov_b32_e32 v113, v112
	s_nop 1
	v_permlane16_swap_b32_e32 v113, v112
	v_add_f32_e32 v112, v112, v113
	v_xor_b32_e32 v113, 32, v184
	v_cmp_lt_i32_e32 vcc, v113, v114
	s_nop 1
	v_cndmask_b32_e32 v113, v184, v113, vcc
	v_lshlrev_b32_e32 v113, 2, v113
	v_mov_b32_e32 v113, v112
	s_nop 1
	v_permlane32_swap_b32_e32 v113, v112
	v_add_f32_e32 v112, v112, v113
	s_and_saveexec_b64 s[28:29], s[2:3]
	s_cbranch_execz .LBB0_313
	v_readlane_b32 s30, v254, 57
	v_lshlrev_b64 v[114:115], 7, v[170:171]
	v_readlane_b32 s31, v254, 58
	s_lshl_b32 s8, s43, 2
	s_waitcnt lgkmcnt(0)
	v_lshl_add_u64 v[114:115], s[30:31], 0, v[114:115]
	v_lshl_add_u64 v[114:115], s[26:27], 2, v[114:115]
	v_lshl_add_u64 v[114:115], v[114:115], 0, s[8:9]
	global_store_dword v[114:115], v112, off

; __device__ __forceinline__ unsigned cvt_pk_bf16(float lo, float hi) { f32x2 v = {lo, hi}; return __builtin_bit_cast(unsigned, __builtin_convertvector(v, bf2_t)); }
;     __device__ __forceinline__ void operator()(const f32x4 (&acc)[2][2][4][2], const Unit& u, int wr, int wc, int fr, int fq) const {
;     ...
;                 for (int bj = 0; bj < 2; ++bj) {
;                     const u32x4 w = raw[m][bj];
;                     const f32x4 r0 = {__uint_as_float(w.x << 16), __uint_as_float(w.x & 0xffff0000u), __uint_as_float(w.y << 16), __uint_as_float(w.y & 0xffff0000u)};
;                     const f32x4 r1 = {__uint_as_float(w.z << 16), __uint_as_float(w.z & 0xffff0000u), __uint_as_float(w.w << 16), __uint_as_float(w.w & 0xffff0000u)};
;                     const f32x4 v0 = r0 + acc[ai][bj][m][0], v1 = r1 + acc[ai][bj][m][1];
;                     if (out32) { *(f32x4*)(out32 + off + bj * HALF) = v0; *(f32x4*)(out32 + off + bj * HALF + 4) = v1; }
;                     if (XB) { u32x4 o; o.x = cvt_pk_bf16(v0[0], v0[1]); o.y = cvt_pk_bf16(v0[2], v0[3]); o.z = cvt_pk_bf16(v1[0], v1[1]); o.w = cvt_pk_bf16(v1[2], v1[3]);
;                               *(u32x4*)(XB + off + bj * HALF) = o;
;                               sq += ((v0[0] * v0[0] + v0[1] * v0[1]) + (v0[2] * v0[2] + v0[3] * v0[3])) + ((v1[0] * v1[0] + v1[1] * v1[1]) + (v1[2] * v1[2] + v1[3] * v1[3])); }
;                 }
;                 if (XB) { sq += __shfl_xor(sq, 16); sq += __shfl_xor(sq, 32); if (fq == 0) SS[(size_t)row * 32 + u.pn * 4 + wc] = sq; }
.LBB0_317:
	v_lshlrev_b32_e32 v106, 16, v144
	v_and_b32_e32 v107, 0xffff0000, v144
	v_lshlrev_b32_e32 v108, 16, v145
	v_and_b32_e32 v109, 0xffff0000, v145
	v_lshlrev_b32_e32 v110, 16, v146
	v_and_b32_e32 v111, 0xffff0000, v146
	v_lshlrev_b32_e32 v114, 16, v147
	v_and_b32_e32 v115, 0xffff0000, v147
	v_pk_add_f32 v[102:103], v[102:103], v[108:109]
	v_pk_add_f32 v[100:101], v[100:101], v[106:107]
	v_pk_add_f32 v[98:99], v[98:99], v[114:115]
	v_pk_add_f32 v[96:97], v[96:97], v[110:111]
	v_cvt_pk_bf16_f32 v106, v100, v101
	v_cvt_pk_bf16_f32 v107, v102, v103
	v_cvt_pk_bf16_f32 v108, v96, v97
	v_cvt_pk_bf16_f32 v109, v98, v99
	s_and_b64 vcc, exec, s[6:7]
	global_store_dwordx4 v[112:113], v[106:109], off offset:256
	s_cbranch_vccnz .LBB0_321
	v_mul_f32_e32 v97, v97, v97
	v_mul_f32_e32 v101, v101, v101
	v_fmac_f32_e32 v97, v96, v96
	v_mul_f32_e32 v96, v99, v99
	v_fmac_f32_e32 v101, v100, v100
	v_mul_f32_e32 v100, v103, v103
	v_fmac_f32_e32 v96, v98, v98
	v_and_b32_e32 v98, 64, v184
	v_fmac_f32_e32 v100, v102, v102
	v_add_f32_e32 v96, v97, v96
	v_xor_b32_e32 v97, 16, v184
	v_add_u32_e32 v98, 64, v98
	v_add_f32_e32 v100, v101, v100
	v_cmp_lt_i32_e32 vcc, v97, v98
	v_add_f32_e32 v96, v100, v96
	v_add_f32_e32 v96, v96, v104
	v_cndmask_b32_e32 v97, v184, v97, vcc
	v_lshlrev_b32_e32 v97, 2, v97
	v_mov_b32_e32 v97, v96
	s_nop 1
	v_permlane16_swap_b32_e32 v97, v96
	v_add_f32_e32 v96, v96, v97
	v_xor_b32_e32 v97, 32, v184
	v_cmp_lt_i32_e32 vcc, v97, v98
	s_nop 1
	v_cndmask_b32_e32 v97, v184, v97, vcc
	v_lshlrev_b32_e32 v97, 2, v97
	v_mov_b32_e32 v97, v96
	s_nop 1
	v_permlane32_swap_b32_e32 v97, v96
	v_add_f32_e32 v96, v96, v97
	s_and_saveexec_b64 s[28:29], s[2:3]
	s_cbranch_execz .LBB0_320
	v_readlane_b32 s30, v254, 57
	v_lshlrev_b64 v[98:99], 7, v[176:177]
	v_readlane_b32 s31, v254, 58
	s_lshl_b32 s8, s43, 2
	s_waitcnt lgkmcnt(0)
	v_lshl_add_u64 v[98:99], s[30:31], 0, v[98:99]
	v_lshl_add_u64 v[98:99], s[26:27], 2, v[98:99]
	v_lshl_add_u64 v[98:99], v[98:99], 0, s[8:9]
	global_store_dword v[98:99], v96, off

; __device__ __forceinline__ unsigned cvt_pk_bf16(float lo, float hi) { f32x2 v = {lo, hi}; return __builtin_bit_cast(unsigned, __builtin_convertvector(v, bf2_t)); }
;     __device__ __forceinline__ void operator()(const f32x4 (&acc)[2][2][4][2], const Unit& u, int wr, int wc, int fr, int fq) const {
;     ...
;                 for (int bj = 0; bj < 2; ++bj) {
;                     const u32x4 w = raw[m][bj];
;                     const f32x4 r0 = {__uint_as_float(w.x << 16), __uint_as_float(w.x & 0xffff0000u), __uint_as_float(w.y << 16), __uint_as_float(w.y & 0xffff0000u)};
;                     const f32x4 r1 = {__uint_as_float(w.z << 16), __uint_as_float(w.z & 0xffff0000u), __uint_as_float(w.w << 16), __uint_as_float(w.w & 0xffff0000u)};
;                     const f32x4 v0 = r0 + acc[ai][bj][m][0], v1 = r1 + acc[ai][bj][m][1];
;                     if (out32) { *(f32x4*)(out32 + off + bj * HALF) = v0; *(f32x4*)(out32 + off + bj * HALF + 4) = v1; }
;                     if (XB) { u32x4 o; o.x = cvt_pk_bf16(v0[0], v0[1]); o.y = cvt_pk_bf16(v0[2], v0[3]); o.z = cvt_pk_bf16(v1[0], v1[1]); o.w = cvt_pk_bf16(v1[2], v1[3]);
;                               *(u32x4*)(XB + off + bj * HALF) = o;
;                               sq += ((v0[0] * v0[0] + v0[1] * v0[1]) + (v0[2] * v0[2] + v0[3] * v0[3])) + ((v1[0] * v1[0] + v1[1] * v1[1]) + (v1[2] * v1[2] + v1[3] * v1[3])); }
;                 }
;                 if (XB) { sq += __shfl_xor(sq, 16); sq += __shfl_xor(sq, 32); if (fq == 0) SS[(size_t)row * 32 + u.pn * 4 + wc] = sq; }
.LBB0_324:
	v_lshlrev_b32_e32 v90, 16, v136
	v_and_b32_e32 v91, 0xffff0000, v136
	v_lshlrev_b32_e32 v92, 16, v137
	v_and_b32_e32 v93, 0xffff0000, v137
	v_lshlrev_b32_e32 v94, 16, v138
	v_and_b32_e32 v95, 0xffff0000, v138
	v_lshlrev_b32_e32 v98, 16, v139
	v_and_b32_e32 v99, 0xffff0000, v139
	v_pk_add_f32 v[86:87], v[86:87], v[92:93]
	v_pk_add_f32 v[84:85], v[84:85], v[90:91]
	v_pk_add_f32 v[82:83], v[82:83], v[98:99]
	v_pk_add_f32 v[80:81], v[80:81], v[94:95]
	v_cvt_pk_bf16_f32 v90, v84, v85
	v_cvt_pk_bf16_f32 v91, v86, v87
	v_cvt_pk_bf16_f32 v92, v80, v81
	v_cvt_pk_bf16_f32 v93, v82, v83
	s_and_b64 vcc, exec, s[6:7]
	global_store_dwordx4 v[96:97], v[90:93], off offset:256
	s_cbranch_vccnz .LBB0_328
	v_mul_f32_e32 v81, v81, v81
	v_mul_f32_e32 v85, v85, v85
	v_fmac_f32_e32 v81, v80, v80
	v_mul_f32_e32 v80, v83, v83
	v_fmac_f32_e32 v85, v84, v84
	v_mul_f32_e32 v84, v87, v87
	v_fmac_f32_e32 v80, v82, v82
	v_and_b32_e32 v82, 64, v184
	v_fmac_f32_e32 v84, v86, v86
	v_add_f32_e32 v80, v81, v80
	v_xor_b32_e32 v81, 16, v184
	v_add_u32_e32 v82, 64, v82
	v_add_f32_e32 v84, v85, v84
	v_cmp_lt_i32_e32 vcc, v81, v82
	v_add_f32_e32 v80, v84, v80
	v_add_f32_e32 v80, v80, v88
	v_cndmask_b32_e32 v81, v184, v81, vcc
	v_lshlrev_b32_e32 v81, 2, v81
	v_mov_b32_e32 v81, v80
	s_nop 1
	v_permlane16_swap_b32_e32 v81, v80
	v_add_f32_e32 v80, v80, v81
	v_xor_b32_e32 v81, 32, v184
	v_cmp_lt_i32_e32 vcc, v81, v82
	s_nop 1
	v_cndmask_b32_e32 v81, v184, v81, vcc
	v_lshlrev_b32_e32 v81, 2, v81
	v_mov_b32_e32 v81, v80
	s_nop 1
	v_permlane32_swap_b32_e32 v81, v80
	v_add_f32_e32 v80, v80, v81
	s_and_saveexec_b64 s[28:29], s[2:3]
	s_cbranch_execz .LBB0_327
	v_readlane_b32 s30, v254, 57
	v_lshlrev_b64 v[82:83], 7, v[174:175]
	v_readlane_b32 s31, v254, 58
	s_lshl_b32 s8, s43, 2
	s_waitcnt lgkmcnt(0)
	v_lshl_add_u64 v[82:83], s[30:31], 0, v[82:83]
	v_lshl_add_u64 v[82:83], s[26:27], 2, v[82:83]
	v_lshl_add_u64 v[82:83], v[82:83], 0, s[8:9]
	global_store_dword v[82:83], v80, off

; __device__ __forceinline__ unsigned cvt_pk_bf16(float lo, float hi) { f32x2 v = {lo, hi}; return __builtin_bit_cast(unsigned, __builtin_convertvector(v, bf2_t)); }
;     __device__ __forceinline__ void operator()(const f32x4 (&acc)[2][2][4][2], const Unit& u, int wr, int wc, int fr, int fq) const {
;     ...
;                 for (int bj = 0; bj < 2; ++bj) {
;                     const u32x4 w = raw[m][bj];
;                     const f32x4 r0 = {__uint_as_float(w.x << 16), __uint_as_float(w.x & 0xffff0000u), __uint_as_float(w.y << 16), __uint_as_float(w.y & 0xffff0000u)};
;                     const f32x4 r1 = {__uint_as_float(w.z << 16), __uint_as_float(w.z & 0xffff0000u), __uint_as_float(w.w << 16), __uint_as_float(w.w & 0xffff0000u)};
;                     const f32x4 v0 = r0 + acc[ai][bj][m][0], v1 = r1 + acc[ai][bj][m][1];
;                     if (out32) { *(f32x4*)(out32 + off + bj * HALF) = v0; *(f32x4*)(out32 + off + bj * HALF + 4) = v1; }
;                     if (XB) { u32x4 o; o.x = cvt_pk_bf16(v0[0], v0[1]); o.y = cvt_pk_bf16(v0[2], v0[3]); o.z = cvt_pk_bf16(v1[0], v1[1]); o.w = cvt_pk_bf16(v1[2], v1[3]);
;                               *(u32x4*)(XB + off + bj * HALF) = o;
;                               sq += ((v0[0] * v0[0] + v0[1] * v0[1]) + (v0[2] * v0[2] + v0[3] * v0[3])) + ((v1[0] * v1[0] + v1[1] * v1[1]) + (v1[2] * v1[2] + v1[3] * v1[3])); }
;                 }
;                 if (XB) { sq += __shfl_xor(sq, 16); sq += __shfl_xor(sq, 32); if (fq == 0) SS[(size_t)row * 32 + u.pn * 4 + wc] = sq; }
.LBB0_331:
	v_lshlrev_b32_e32 v74, 16, v128
	v_and_b32_e32 v75, 0xffff0000, v128
	v_lshlrev_b32_e32 v76, 16, v129
	v_and_b32_e32 v77, 0xffff0000, v129
	v_lshlrev_b32_e32 v78, 16, v130
	v_and_b32_e32 v79, 0xffff0000, v130
	v_lshlrev_b32_e32 v82, 16, v131
	v_and_b32_e32 v83, 0xffff0000, v131
	v_pk_add_f32 v[70:71], v[70:71], v[76:77]
	v_pk_add_f32 v[68:69], v[68:69], v[74:75]
	v_pk_add_f32 v[66:67], v[66:67], v[82:83]
	v_pk_add_f32 v[64:65], v[64:65], v[78:79]
	v_cvt_pk_bf16_f32 v74, v68, v69
	v_cvt_pk_bf16_f32 v75, v70, v71
	v_cvt_pk_bf16_f32 v76, v64, v65
	v_cvt_pk_bf16_f32 v77, v66, v67
	s_and_b64 vcc, exec, s[6:7]
	global_store_dwordx4 v[80:81], v[74:77], off offset:256
	s_cbranch_vccnz .LBB0_335
	v_mul_f32_e32 v65, v65, v65
	v_mul_f32_e32 v69, v69, v69
	v_fmac_f32_e32 v65, v64, v64
	v_mul_f32_e32 v64, v67, v67
	v_fmac_f32_e32 v69, v68, v68
	v_mul_f32_e32 v68, v71, v71
	v_fmac_f32_e32 v64, v66, v66
	v_and_b32_e32 v66, 64, v184
	v_fmac_f32_e32 v68, v70, v70
	v_add_f32_e32 v64, v65, v64
	v_xor_b32_e32 v65, 16, v184
	v_add_u32_e32 v66, 64, v66
	v_add_f32_e32 v68, v69, v68
	v_cmp_lt_i32_e32 vcc, v65, v66
	v_add_f32_e32 v64, v68, v64
	v_add_f32_e32 v64, v64, v72
	v_cndmask_b32_e32 v65, v184, v65, vcc
	v_lshlrev_b32_e32 v65, 2, v65
	v_mov_b32_e32 v65, v64
	s_nop 1
	v_permlane16_swap_b32_e32 v65, v64
	v_add_f32_e32 v64, v64, v65
	v_xor_b32_e32 v65, 32, v184
	v_cmp_lt_i32_e32 vcc, v65, v66
	s_nop 1
	v_cndmask_b32_e32 v65, v184, v65, vcc
	v_lshlrev_b32_e32 v65, 2, v65
	v_mov_b32_e32 v65, v64
	s_nop 1
	v_permlane32_swap_b32_e32 v65, v64
	v_add_f32_e32 v64, v64, v65
	s_and_saveexec_b64 s[28:29], s[2:3]
	s_cbranch_execz .LBB0_334
	v_readlane_b32 s30, v254, 57
	v_lshlrev_b64 v[66:67], 7, v[172:173]
	v_readlane_b32 s31, v254, 58
	s_lshl_b32 s8, s43, 2
	s_waitcnt lgkmcnt(0)
	v_lshl_add_u64 v[66:67], s[30:31], 0, v[66:67]
	v_lshl_add_u64 v[66:67], s[26:27], 2, v[66:67]
	v_lshl_add_u64 v[66:67], v[66:67], 0, s[8:9]
	global_store_dword v[66:67], v64, off

; __device__ __forceinline__ unsigned cvt_pk_bf16(float lo, float hi) { f32x2 v = {lo, hi}; return __builtin_bit_cast(unsigned, __builtin_convertvector(v, bf2_t)); }
;     __device__ __forceinline__ void operator()(const f32x4 (&acc)[2][2][4][2], const Unit& u, int wr, int wc, int fr, int fq) const {
;     ...
;                 for (int bj = 0; bj < 2; ++bj) {
;                     const u32x4 w = raw[m][bj];
;                     const f32x4 r0 = {__uint_as_float(w.x << 16), __uint_as_float(w.x & 0xffff0000u), __uint_as_float(w.y << 16), __uint_as_float(w.y & 0xffff0000u)};
;                     const f32x4 r1 = {__uint_as_float(w.z << 16), __uint_as_float(w.z & 0xffff0000u), __uint_as_float(w.w << 16), __uint_as_float(w.w & 0xffff0000u)};
;                     const f32x4 v0 = r0 + acc[ai][bj][m][0], v1 = r1 + acc[ai][bj][m][1];
;                     if (out32) { *(f32x4*)(out32 + off + bj * HALF) = v0; *(f32x4*)(out32 + off + bj * HALF + 4) = v1; }
;                     if (XB) { u32x4 o; o.x = cvt_pk_bf16(v0[0], v0[1]); o.y = cvt_pk_bf16(v0[2], v0[3]); o.z = cvt_pk_bf16(v1[0], v1[1]); o.w = cvt_pk_bf16(v1[2], v1[3]);
;                               *(u32x4*)(XB + off + bj * HALF) = o;
;                               sq += ((v0[0] * v0[0] + v0[1] * v0[1]) + (v0[2] * v0[2] + v0[3] * v0[3])) + ((v1[0] * v1[0] + v1[1] * v1[1]) + (v1[2] * v1[2] + v1[3] * v1[3])); }
;                 }
;                 if (XB) { sq += __shfl_xor(sq, 16); sq += __shfl_xor(sq, 32); if (fq == 0) SS[(size_t)row * 32 + u.pn * 4 + wc] = sq; }
.LBB0_338:
	v_lshlrev_b32_e32 v58, 16, v88
	v_and_b32_e32 v59, 0xffff0000, v88
	v_lshlrev_b32_e32 v60, 16, v89
	v_and_b32_e32 v61, 0xffff0000, v89
	v_lshlrev_b32_e32 v62, 16, v90
	v_and_b32_e32 v63, 0xffff0000, v90
	v_lshlrev_b32_e32 v88, 16, v91
	v_and_b32_e32 v89, 0xffff0000, v91
	v_pk_add_f32 v[54:55], v[54:55], v[60:61]
	v_pk_add_f32 v[52:53], v[52:53], v[58:59]
	v_pk_add_f32 v[50:51], v[50:51], v[88:89]
	v_pk_add_f32 v[48:49], v[48:49], v[62:63]
	v_cvt_pk_bf16_f32 v58, v52, v53
	v_cvt_pk_bf16_f32 v59, v54, v55
	v_cvt_pk_bf16_f32 v60, v48, v49
	v_cvt_pk_bf16_f32 v61, v50, v51
	s_and_b64 vcc, exec, s[6:7]
	global_store_dwordx4 v[100:101], v[58:61], off offset:256
	s_cbranch_vccnz .LBB0_342
	v_mul_f32_e32 v49, v49, v49
	v_mul_f32_e32 v53, v53, v53
	v_fmac_f32_e32 v49, v48, v48
	v_mul_f32_e32 v48, v51, v51
	v_fmac_f32_e32 v53, v52, v52
	v_mul_f32_e32 v52, v55, v55
	v_fmac_f32_e32 v48, v50, v50
	v_and_b32_e32 v50, 64, v184
	v_fmac_f32_e32 v52, v54, v54
	v_add_f32_e32 v48, v49, v48
	v_xor_b32_e32 v49, 16, v184
	v_add_u32_e32 v50, 64, v50
	v_add_f32_e32 v52, v53, v52
	v_cmp_lt_i32_e32 vcc, v49, v50
	v_add_f32_e32 v48, v52, v48
	v_add_f32_e32 v48, v48, v56
	v_cndmask_b32_e32 v49, v184, v49, vcc
	v_lshlrev_b32_e32 v49, 2, v49
	v_mov_b32_e32 v49, v48
	s_nop 1
	v_permlane16_swap_b32_e32 v49, v48
	v_add_f32_e32 v48, v48, v49
	v_xor_b32_e32 v49, 32, v184
	v_cmp_lt_i32_e32 vcc, v49, v50
	s_nop 1
	v_cndmask_b32_e32 v49, v184, v49, vcc
	v_lshlrev_b32_e32 v49, 2, v49
	v_mov_b32_e32 v49, v48
	s_nop 1
	v_permlane32_swap_b32_e32 v49, v48
	v_add_f32_e32 v48, v48, v49
	s_and_saveexec_b64 s[28:29], s[2:3]
	s_cbranch_execz .LBB0_341
	v_readlane_b32 s30, v254, 57
	v_lshlrev_b64 v[50:51], 7, v[98:99]
	v_readlane_b32 s31, v254, 58
	s_lshl_b32 s8, s43, 2
	s_waitcnt lgkmcnt(0)
	v_lshl_add_u64 v[50:51], s[30:31], 0, v[50:51]
	v_lshl_add_u64 v[50:51], s[26:27], 2, v[50:51]
	v_lshl_add_u64 v[50:51], v[50:51], 0, s[8:9]
	global_store_dword v[50:51], v48, off

; __device__ __forceinline__ unsigned cvt_pk_bf16(float lo, float hi) { f32x2 v = {lo, hi}; return __builtin_bit_cast(unsigned, __builtin_convertvector(v, bf2_t)); }
;     __device__ __forceinline__ void operator()(const f32x4 (&acc)[2][2][4][2], const Unit& u, int wr, int wc, int fr, int fq) const {
;     ...
;                 for (int bj = 0; bj < 2; ++bj) {
;                     const u32x4 w = raw[m][bj];
;                     const f32x4 r0 = {__uint_as_float(w.x << 16), __uint_as_float(w.x & 0xffff0000u), __uint_as_float(w.y << 16), __uint_as_float(w.y & 0xffff0000u)};
;                     const f32x4 r1 = {__uint_as_float(w.z << 16), __uint_as_float(w.z & 0xffff0000u), __uint_as_float(w.w << 16), __uint_as_float(w.w & 0xffff0000u)};
;                     const f32x4 v0 = r0 + acc[ai][bj][m][0], v1 = r1 + acc[ai][bj][m][1];
;                     if (out32) { *(f32x4*)(out32 + off + bj * HALF) = v0; *(f32x4*)(out32 + off + bj * HALF + 4) = v1; }
;                     if (XB) { u32x4 o; o.x = cvt_pk_bf16(v0[0], v0[1]); o.y = cvt_pk_bf16(v0[2], v0[3]); o.z = cvt_pk_bf16(v1[0], v1[1]); o.w = cvt_pk_bf16(v1[2], v1[3]);
;                               *(u32x4*)(XB + off + bj * HALF) = o;
;                               sq += ((v0[0] * v0[0] + v0[1] * v0[1]) + (v0[2] * v0[2] + v0[3] * v0[3])) + ((v1[0] * v1[0] + v1[1] * v1[1]) + (v1[2] * v1[2] + v1[3] * v1[3])); }
;                 }
;                 if (XB) { sq += __shfl_xor(sq, 16); sq += __shfl_xor(sq, 32); if (fq == 0) SS[(size_t)row * 32 + u.pn * 4 + wc] = sq; }
.LBB0_345:
	v_lshlrev_b32_e32 v42, 16, v80
	v_and_b32_e32 v43, 0xffff0000, v80
	v_lshlrev_b32_e32 v44, 16, v81
	v_and_b32_e32 v45, 0xffff0000, v81
	v_lshlrev_b32_e32 v46, 16, v82
	v_and_b32_e32 v47, 0xffff0000, v82
	v_lshlrev_b32_e32 v50, 16, v83
	v_and_b32_e32 v51, 0xffff0000, v83
	v_pk_add_f32 v[38:39], v[38:39], v[44:45]
	v_pk_add_f32 v[36:37], v[36:37], v[42:43]
	v_pk_add_f32 v[34:35], v[34:35], v[50:51]
	v_pk_add_f32 v[32:33], v[32:33], v[46:47]
	v_cvt_pk_bf16_f32 v42, v36, v37
	v_cvt_pk_bf16_f32 v43, v38, v39
	v_cvt_pk_bf16_f32 v44, v32, v33
	v_cvt_pk_bf16_f32 v45, v34, v35
	s_and_b64 vcc, exec, s[6:7]
	global_store_dwordx4 v[48:49], v[42:45], off offset:256
	s_cbranch_vccnz .LBB0_349
	v_mul_f32_e32 v33, v33, v33
	v_mul_f32_e32 v37, v37, v37
	v_fmac_f32_e32 v33, v32, v32
	v_mul_f32_e32 v32, v35, v35
	v_fmac_f32_e32 v37, v36, v36
	v_mul_f32_e32 v36, v39, v39
	v_fmac_f32_e32 v32, v34, v34
	v_and_b32_e32 v34, 64, v184
	v_fmac_f32_e32 v36, v38, v38
	v_add_f32_e32 v32, v33, v32
	v_xor_b32_e32 v33, 16, v184
	v_add_u32_e32 v34, 64, v34
	v_add_f32_e32 v36, v37, v36
	v_cmp_lt_i32_e32 vcc, v33, v34
	v_add_f32_e32 v32, v36, v32
	v_add_f32_e32 v32, v32, v40
	v_cndmask_b32_e32 v33, v184, v33, vcc
	v_lshlrev_b32_e32 v33, 2, v33
	v_mov_b32_e32 v33, v32
	s_nop 1
	v_permlane16_swap_b32_e32 v33, v32
	v_add_f32_e32 v32, v32, v33
	v_xor_b32_e32 v33, 32, v184
	v_cmp_lt_i32_e32 vcc, v33, v34
	s_nop 1
	v_cndmask_b32_e32 v33, v184, v33, vcc
	v_lshlrev_b32_e32 v33, 2, v33
	v_mov_b32_e32 v33, v32
	s_nop 1
	v_permlane32_swap_b32_e32 v33, v32
	v_add_f32_e32 v32, v32, v33
	s_and_saveexec_b64 s[28:29], s[2:3]
	s_cbranch_execz .LBB0_348
	v_readlane_b32 s30, v254, 57
	v_lshlrev_b64 v[34:35], 7, v[96:97]
	v_readlane_b32 s31, v254, 58
	s_lshl_b32 s8, s43, 2
	s_waitcnt lgkmcnt(0)
	v_lshl_add_u64 v[34:35], s[30:31], 0, v[34:35]
	v_lshl_add_u64 v[34:35], s[26:27], 2, v[34:35]
	v_lshl_add_u64 v[34:35], v[34:35], 0, s[8:9]
	global_store_dword v[34:35], v32, off

; __device__ __forceinline__ unsigned cvt_pk_bf16(float lo, float hi) { f32x2 v = {lo, hi}; return __builtin_bit_cast(unsigned, __builtin_convertvector(v, bf2_t)); }
;     __device__ __forceinline__ void operator()(const f32x4 (&acc)[2][2][4][2], const Unit& u, int wr, int wc, int fr, int fq) const {
;     ...
;                 for (int bj = 0; bj < 2; ++bj) {
;                     const u32x4 w = raw[m][bj];
;                     const f32x4 r0 = {__uint_as_float(w.x << 16), __uint_as_float(w.x & 0xffff0000u), __uint_as_float(w.y << 16), __uint_as_float(w.y & 0xffff0000u)};
;                     const f32x4 r1 = {__uint_as_float(w.z << 16), __uint_as_float(w.z & 0xffff0000u), __uint_as_float(w.w << 16), __uint_as_float(w.w & 0xffff0000u)};
;                     const f32x4 v0 = r0 + acc[ai][bj][m][0], v1 = r1 + acc[ai][bj][m][1];
;                     if (out32) { *(f32x4*)(out32 + off + bj * HALF) = v0; *(f32x4*)(out32 + off + bj * HALF + 4) = v1; }
;                     if (XB) { u32x4 o; o.x = cvt_pk_bf16(v0[0], v0[1]); o.y = cvt_pk_bf16(v0[2], v0[3]); o.z = cvt_pk_bf16(v1[0], v1[1]); o.w = cvt_pk_bf16(v1[2], v1[3]);
;                               *(u32x4*)(XB + off + bj * HALF) = o;
;                               sq += ((v0[0] * v0[0] + v0[1] * v0[1]) + (v0[2] * v0[2] + v0[3] * v0[3])) + ((v1[0] * v1[0] + v1[1] * v1[1]) + (v1[2] * v1[2] + v1[3] * v1[3])); }
;                 }
;                 if (XB) { sq += __shfl_xor(sq, 16); sq += __shfl_xor(sq, 32); if (fq == 0) SS[(size_t)row * 32 + u.pn * 4 + wc] = sq; }
.LBB0_352:
	v_lshlrev_b32_e32 v26, 16, v72
	v_and_b32_e32 v27, 0xffff0000, v72
	v_lshlrev_b32_e32 v28, 16, v73
	v_and_b32_e32 v29, 0xffff0000, v73
	v_lshlrev_b32_e32 v30, 16, v74
	v_and_b32_e32 v31, 0xffff0000, v74
	v_lshlrev_b32_e32 v34, 16, v75
	v_and_b32_e32 v35, 0xffff0000, v75
	v_pk_add_f32 v[22:23], v[22:23], v[28:29]
	v_pk_add_f32 v[20:21], v[20:21], v[26:27]
	v_pk_add_f32 v[18:19], v[18:19], v[34:35]
	v_pk_add_f32 v[16:17], v[16:17], v[30:31]
	v_cvt_pk_bf16_f32 v26, v20, v21
	v_cvt_pk_bf16_f32 v27, v22, v23
	v_cvt_pk_bf16_f32 v28, v16, v17
	v_cvt_pk_bf16_f32 v29, v18, v19
	s_and_b64 vcc, exec, s[6:7]
	global_store_dwordx4 v[32:33], v[26:29], off offset:256
	s_cbranch_vccnz .LBB0_356
	v_mul_f32_e32 v17, v17, v17
	v_mul_f32_e32 v21, v21, v21
	v_fmac_f32_e32 v17, v16, v16
	v_mul_f32_e32 v16, v19, v19
	v_fmac_f32_e32 v21, v20, v20
	v_mul_f32_e32 v20, v23, v23
	v_fmac_f32_e32 v16, v18, v18
	v_and_b32_e32 v18, 64, v184
	v_fmac_f32_e32 v20, v22, v22
	v_add_f32_e32 v16, v17, v16
	v_xor_b32_e32 v17, 16, v184
	v_add_u32_e32 v18, 64, v18
	v_add_f32_e32 v20, v21, v20
	v_cmp_lt_i32_e32 vcc, v17, v18
	v_add_f32_e32 v16, v20, v16
	v_add_f32_e32 v16, v16, v24
	v_cndmask_b32_e32 v17, v184, v17, vcc
	v_lshlrev_b32_e32 v17, 2, v17
	v_mov_b32_e32 v17, v16
	s_nop 1
	v_permlane16_swap_b32_e32 v17, v16
	v_add_f32_e32 v16, v16, v17
	v_xor_b32_e32 v17, 32, v184
	v_cmp_lt_i32_e32 vcc, v17, v18
	s_nop 1
	v_cndmask_b32_e32 v17, v184, v17, vcc
	v_lshlrev_b32_e32 v17, 2, v17
	v_mov_b32_e32 v17, v16
	s_nop 1
	v_permlane32_swap_b32_e32 v17, v16
	v_add_f32_e32 v16, v16, v17
	s_and_saveexec_b64 s[28:29], s[2:3]
	s_cbranch_execz .LBB0_355
	v_readlane_b32 s30, v254, 57
	v_lshlrev_b64 v[18:19], 7, v[94:95]
	v_readlane_b32 s31, v254, 58
	s_lshl_b32 s8, s43, 2
	s_waitcnt lgkmcnt(0)
	v_lshl_add_u64 v[18:19], s[30:31], 0, v[18:19]
	v_lshl_add_u64 v[18:19], s[26:27], 2, v[18:19]
	v_lshl_add_u64 v[18:19], v[18:19], 0, s[8:9]
	global_store_dword v[18:19], v16, off

;     __device__ __forceinline__ void operator()(const f32x4 (&acc)[2][2][4][2], const Unit& u, int wr, int wc, int fr, int fq) const {
;     ...
;         for (int ai = 0; ai < 2; ++ai)
; #pragma unroll
;             for (int m = 0; m < 4; ++m) {
;                 float sq = 0.f;
; #pragma unroll
;                 for (int bj = 0; bj < 2; ++bj)
; #pragma unroll
;                     for (int n = 0; n < 2; ++n) { const f32x4 v = acc[ai][bj][m][n]; sq += (v[0] * v[0] + v[1] * v[1]) + (v[2] * v[2] + v[3] * v[3]); }
;                 sq += __shfl_xor(sq, 16); sq += __shfl_xor(sq, 32);
;                 if (fq == 0) xl[(ai * HALF + wr * 64 + m * 16 + fr) * 4 + wc] = sq * rsv[ai][m] * rsv[ai][m];
.LBB0_499:
	s_or_b64 exec, exec, s[0:1]
	v_mul_f32_e32 v131, v117, v117
	s_waitcnt lgkmcnt(0)
	v_mul_f32_e32 v132, v119, v119
	v_fmac_f32_e32 v131, v116, v116
	v_fmac_f32_e32 v132, v118, v118
	v_add_f32_e32 v131, v131, v132
	v_mul_f32_e32 v132, v109, v109
	v_mul_f32_e32 v133, v111, v111
	v_fmac_f32_e32 v132, v108, v108
	v_fmac_f32_e32 v133, v110, v110
	v_add_f32_e32 v132, v132, v133
	v_add_f32_e32 v131, v131, v132
	v_mul_f32_e32 v132, v97, v97
	v_mul_f32_e32 v133, v99, v99
	v_fmac_f32_e32 v132, v96, v96
	v_fmac_f32_e32 v133, v98, v98
	v_add_f32_e32 v132, v132, v133
	v_add_f32_e32 v131, v131, v132
	v_mul_f32_e32 v132, v89, v89
	v_mul_f32_e32 v133, v91, v91
	v_fmac_f32_e32 v132, v88, v88
	v_fmac_f32_e32 v133, v90, v90
	v_add_f32_e32 v132, v132, v133
	v_add_f32_e32 v131, v131, v132
	v_mov_b32_e32 v132, v131
	s_nop 1
	v_permlane16_swap_b32_e32 v132, v131
	v_add_f32_e32 v131, v131, v132
	v_mov_b32_e32 v132, v131
	s_nop 1
	v_permlane32_swap_b32_e32 v132, v131
	v_add_f32_e32 v131, v131, v132
	s_and_saveexec_b64 s[0:1], s[2:3]
	s_cbranch_execz .LBB0_501
	s_waitcnt lgkmcnt(0)
	s_waitcnt vmcnt(0)
	v_mul_f32_e32 v131, v178, v131
	v_mul_f32_e32 v131, v178, v131
	ds_write_b32 v129, v131 offset:256
.LBB0_501:
	s_or_b64 exec, exec, s[0:1]
	v_mul_f32_e32 v131, v101, v101
	s_waitcnt lgkmcnt(0)
	v_mul_f32_e32 v132, v103, v103
	v_fmac_f32_e32 v131, v100, v100
	v_fmac_f32_e32 v132, v102, v102
	v_add_f32_e32 v131, v131, v132
	v_mul_f32_e32 v132, v93, v93
	v_mul_f32_e32 v133, v95, v95
	v_fmac_f32_e32 v132, v92, v92
	v_fmac_f32_e32 v133, v94, v94
	v_add_f32_e32 v132, v132, v133
	v_add_f32_e32 v131, v131, v132
	v_mul_f32_e32 v132, v81, v81
	v_mul_f32_e32 v133, v83, v83
	v_fmac_f32_e32 v132, v80, v80
	v_fmac_f32_e32 v133, v82, v82
	v_add_f32_e32 v132, v132, v133
	v_add_f32_e32 v131, v131, v132
	v_mul_f32_e32 v132, v73, v73
	v_mul_f32_e32 v133, v75, v75
	v_fmac_f32_e32 v132, v72, v72
	v_fmac_f32_e32 v133, v74, v74
	v_add_f32_e32 v132, v132, v133
	v_add_f32_e32 v131, v131, v132
	v_mov_b32_e32 v132, v131
	s_nop 1
	v_permlane16_swap_b32_e32 v132, v131
	v_add_f32_e32 v131, v131, v132
	v_mov_b32_e32 v132, v131
	s_nop 1
	v_permlane32_swap_b32_e32 v132, v131
	v_add_f32_e32 v131, v131, v132
	s_and_saveexec_b64 s[0:1], s[2:3]
	s_cbranch_execz .LBB0_503
	s_waitcnt lgkmcnt(0)
	s_waitcnt vmcnt(0)
	v_mul_f32_e32 v131, v174, v131
	v_mul_f32_e32 v131, v174, v131
	ds_write_b32 v129, v131 offset:512
.LBB0_503:
	s_or_b64 exec, exec, s[0:1]
	v_mul_f32_e32 v131, v85, v85
	s_waitcnt lgkmcnt(0)
	v_mul_f32_e32 v132, v87, v87
	v_fmac_f32_e32 v131, v84, v84
	v_fmac_f32_e32 v132, v86, v86
	v_add_f32_e32 v131, v131, v132
	v_mul_f32_e32 v132, v77, v77
	v_mul_f32_e32 v133, v79, v79
	v_fmac_f32_e32 v132, v76, v76
	v_fmac_f32_e32 v133, v78, v78
	v_add_f32_e32 v132, v132, v133
	v_add_f32_e32 v131, v131, v132
	v_mul_f32_e32 v132, v69, v69
	v_mul_f32_e32 v133, v71, v71
	v_fmac_f32_e32 v132, v68, v68
	v_fmac_f32_e32 v133, v70, v70
	v_add_f32_e32 v132, v132, v133
	v_add_f32_e32 v131, v131, v132
	v_mul_f32_e32 v132, v65, v65
	v_mul_f32_e32 v133, v67, v67
	v_fmac_f32_e32 v132, v64, v64
	v_fmac_f32_e32 v133, v66, v66
	v_add_f32_e32 v132, v132, v133
	v_add_f32_e32 v131, v131, v132
	v_mov_b32_e32 v132, v131
	s_nop 1
	v_permlane16_swap_b32_e32 v132, v131
	v_add_f32_e32 v131, v131, v132
	v_mov_b32_e32 v132, v131
	s_nop 1
	v_permlane32_swap_b32_e32 v132, v131
	v_add_f32_e32 v131, v131, v132
	s_and_saveexec_b64 s[0:1], s[2:3]
	s_cbranch_execz .LBB0_505
	s_waitcnt lgkmcnt(0)
	s_waitcnt vmcnt(0)
	v_mul_f32_e32 v131, v170, v131
	v_mul_f32_e32 v131, v170, v131
	ds_write_b32 v129, v131 offset:768
;     __device__ __forceinline__ void operator()(const f32x4 (&acc)[2][2][4][2], const Unit& u, int wr, int wc, int fr, int fq) const {
;     ...
;         for (int ai = 0; ai < 2; ++ai)
; #pragma unroll
;             for (int m = 0; m < 4; ++m) {
;                 float sq = 0.f;
; #pragma unroll
;                 for (int bj = 0; bj < 2; ++bj)
; #pragma unroll
;                     for (int n = 0; n < 2; ++n) { const f32x4 v = acc[ai][bj][m][n]; sq += (v[0] * v[0] + v[1] * v[1]) + (v[2] * v[2] + v[3] * v[3]); }
;                 sq += __shfl_xor(sq, 16); sq += __shfl_xor(sq, 32);
;                 if (fq == 0) xl[(ai * HALF + wr * 64 + m * 16 + fr) * 4 + wc] = sq * rsv[ai][m] * rsv[ai][m];
.LBB0_505:
	s_or_b64 exec, exec, s[0:1]
	v_mul_f32_e32 v131, v61, v61
	s_waitcnt lgkmcnt(0)
	v_mul_f32_e32 v132, v63, v63
	v_fmac_f32_e32 v131, v60, v60
	v_fmac_f32_e32 v132, v62, v62
	v_add_f32_e32 v131, v131, v132
	v_mul_f32_e32 v132, v57, v57
	v_mul_f32_e32 v133, v59, v59
	v_fmac_f32_e32 v132, v56, v56
	v_fmac_f32_e32 v133, v58, v58
	v_add_f32_e32 v132, v132, v133
	v_add_f32_e32 v131, v131, v132
	v_mul_f32_e32 v132, v49, v49
	v_mul_f32_e32 v133, v51, v51
	v_fmac_f32_e32 v132, v48, v48
	v_fmac_f32_e32 v133, v50, v50
	v_add_f32_e32 v132, v132, v133
	v_add_f32_e32 v131, v131, v132
	v_mul_f32_e32 v132, v41, v41
	v_mul_f32_e32 v133, v43, v43
	v_fmac_f32_e32 v132, v40, v40
	v_fmac_f32_e32 v133, v42, v42
	v_add_f32_e32 v132, v132, v133
	v_add_f32_e32 v131, v131, v132
	v_mov_b32_e32 v132, v131
	s_nop 1
	v_permlane16_swap_b32_e32 v132, v131
	v_add_f32_e32 v131, v131, v132
	v_mov_b32_e32 v132, v131
	s_nop 1
	v_permlane32_swap_b32_e32 v132, v131
	v_add_f32_e32 v131, v131, v132
	s_and_saveexec_b64 s[0:1], s[2:3]
	s_cbranch_execz .LBB0_507
	s_waitcnt lgkmcnt(0)
	s_waitcnt vmcnt(0)
	v_mul_f32_e32 v131, v168, v131
	v_mul_f32_e32 v131, v168, v131
	ds_write_b32 v129, v131 offset:2048
.LBB0_507:
	s_or_b64 exec, exec, s[0:1]
	v_mul_f32_e32 v131, v53, v53
	s_waitcnt lgkmcnt(0)
	v_mul_f32_e32 v132, v55, v55
	v_fmac_f32_e32 v131, v52, v52
	v_fmac_f32_e32 v132, v54, v54
	v_add_f32_e32 v131, v131, v132
	v_mul_f32_e32 v132, v45, v45
	v_mul_f32_e32 v133, v47, v47
	v_fmac_f32_e32 v132, v44, v44
	v_fmac_f32_e32 v133, v46, v46
	v_add_f32_e32 v132, v132, v133
	v_add_f32_e32 v131, v131, v132
	v_mul_f32_e32 v132, v33, v33
	v_mul_f32_e32 v133, v35, v35
	v_fmac_f32_e32 v132, v32, v32
	v_fmac_f32_e32 v133, v34, v34
	v_add_f32_e32 v132, v132, v133
	v_add_f32_e32 v131, v131, v132
	v_mul_f32_e32 v132, v25, v25
	v_mul_f32_e32 v133, v27, v27
	v_fmac_f32_e32 v132, v24, v24
	v_fmac_f32_e32 v133, v26, v26
	v_add_f32_e32 v132, v132, v133
	v_add_f32_e32 v131, v131, v132
	v_mov_b32_e32 v132, v131
	s_nop 1
	v_permlane16_swap_b32_e32 v132, v131
	v_add_f32_e32 v131, v131, v132
	v_mov_b32_e32 v132, v131
	s_nop 1
	v_permlane32_swap_b32_e32 v132, v131
	v_add_f32_e32 v131, v131, v132
	s_and_saveexec_b64 s[0:1], s[2:3]
	s_cbranch_execz .LBB0_509
	s_waitcnt lgkmcnt(0)
	s_waitcnt vmcnt(0)
	v_mul_f32_e32 v131, v166, v131
	v_mul_f32_e32 v131, v166, v131
	ds_write_b32 v129, v131 offset:2304
.LBB0_509:
	s_or_b64 exec, exec, s[0:1]
	v_mul_f32_e32 v131, v37, v37
	s_waitcnt lgkmcnt(0)
	v_mul_f32_e32 v132, v39, v39
	v_fmac_f32_e32 v131, v36, v36
	v_fmac_f32_e32 v132, v38, v38
	v_add_f32_e32 v131, v131, v132
	v_mul_f32_e32 v132, v29, v29
	v_mul_f32_e32 v133, v31, v31
	v_fmac_f32_e32 v132, v28, v28
	v_fmac_f32_e32 v133, v30, v30
	v_add_f32_e32 v132, v132, v133
	v_add_f32_e32 v131, v131, v132
	v_mul_f32_e32 v132, v17, v17
	v_mul_f32_e32 v133, v19, v19
	v_fmac_f32_e32 v132, v16, v16
	v_fmac_f32_e32 v133, v18, v18
	v_add_f32_e32 v132, v132, v133
	v_add_f32_e32 v131, v131, v132
	v_mul_f32_e32 v132, v9, v9
	v_mul_f32_e32 v133, v11, v11
	v_fmac_f32_e32 v132, v8, v8
	v_fmac_f32_e32 v133, v10, v10
	v_add_f32_e32 v132, v132, v133
	v_add_f32_e32 v131, v131, v132
	v_mov_b32_e32 v132, v131
	s_nop 1
	v_permlane16_swap_b32_e32 v132, v131
	v_add_f32_e32 v131, v131, v132
	v_mov_b32_e32 v132, v131
	s_nop 1
	v_permlane32_swap_b32_e32 v132, v131
	v_add_f32_e32 v131, v131, v132
	s_and_saveexec_b64 s[0:1], s[2:3]
	s_cbranch_execz .LBB0_511
	s_waitcnt lgkmcnt(0)
	s_waitcnt vmcnt(0)
	v_mul_f32_e32 v131, v164, v131
	v_mul_f32_e32 v131, v164, v131
	ds_write_b32 v129, v131 offset:2560

; __device__ __forceinline__ unsigned cvt_pk_bf16(float lo, float hi) { f32x2 v = {lo, hi}; return __builtin_bit_cast(unsigned, __builtin_convertvector(v, bf2_t)); }
;     __device__ __forceinline__ void operator()(const f32x4 (&acc)[2][2][4][2], const Unit& u, int wr, int wc, int fr, int fq) const {
;     ...
;                 for (int bj = 0; bj < 2; ++bj) raw[m][bj] = *(const u32x4*)(base16 + (size_t)(row0 + ai * HALF + m * 16) * 2048 + col0 + bj * HALF);
; #pragma unroll
;             for (int m = 0; m < 4; ++m) {
;                 const int row = row0 + ai * HALF + m * 16;
;                 const size_t off = (size_t)row * 2048 + col0;
;                 float sq = 0.f;
; #pragma unroll
;                 for (int bj = 0; bj < 2; ++bj) {
;                     const u32x4 w = raw[m][bj];
;                     const f32x4 r0 = {__uint_as_float(w.x << 16), __uint_as_float(w.x & 0xffff0000u), __uint_as_float(w.y << 16), __uint_as_float(w.y & 0xffff0000u)};
;                     const f32x4 r1 = {__uint_as_float(w.z << 16), __uint_as_float(w.z & 0xffff0000u), __uint_as_float(w.w << 16), __uint_as_float(w.w & 0xffff0000u)};
;                     const f32x4 v0 = r0 + acc[ai][bj][m][0], v1 = r1 + acc[ai][bj][m][1];
;                     if (out32) { *(f32x4*)(out32 + off + bj * HALF) = v0; *(f32x4*)(out32 + off + bj * HALF + 4) = v1; }
;                     if (XB) { u32x4 o; o.x = cvt_pk_bf16(v0[0], v0[1]); o.y = cvt_pk_bf16(v0[2], v0[3]); o.z = cvt_pk_bf16(v1[0], v1[1]); o.w = cvt_pk_bf16(v1[2], v1[3]);
;                               *(u32x4*)(XB + off + bj * HALF) = o;
;                               sq += ((v0[0] * v0[0] + v0[1] * v0[1]) + (v0[2] * v0[2] + v0[3] * v0[3])) + ((v1[0] * v1[0] + v1[1] * v1[1]) + (v1[2] * v1[2] + v1[3] * v1[3])); }
;                 }
;                 if (XB) { sq += __shfl_xor(sq, 16); sq += __shfl_xor(sq, 32); if (fq == 0) SS[(size_t)row * 32 + u.pn * 4 + wc] = sq; }
.LBB0_766:
	v_lshl_or_b32 v128, s6, 8, v180
	v_lshl_add_u32 v170, s8, 8, v178
	v_ashrrev_i32_e32 v129, 31, v128
	v_lshlrev_b64 v[194:195], 1, v[128:129]
	v_ashrrev_i32_e32 v171, 31, v170
	v_lshl_add_u64 v[168:169], s[74:75], 0, v[194:195]
	v_lshlrev_b64 v[198:199], 12, v[170:171]
	v_or_b32_e32 v176, 16, v170
	v_or_b32_e32 v174, 32, v170
	v_lshl_add_u64 v[128:129], v[168:169], 0, v[198:199]
	v_or_b32_e32 v172, 48, v170
	v_ashrrev_i32_e32 v177, 31, v176
	v_ashrrev_i32_e32 v175, 31, v174
	global_load_dwordx4 v[186:189], v[128:129], off
	global_load_dwordx4 v[190:193], v[128:129], off offset:256
	v_ashrrev_i32_e32 v173, 31, v172
	v_lshlrev_b64 v[128:129], 12, v[176:177]
	v_lshlrev_b64 v[130:131], 12, v[174:175]
	v_lshlrev_b64 v[132:133], 12, v[172:173]
	v_lshl_add_u64 v[128:129], v[168:169], 0, v[128:129]
	v_lshl_add_u64 v[130:131], v[168:169], 0, v[130:131]
	v_lshl_add_u64 v[200:201], v[168:169], 0, v[132:133]
	global_load_dwordx4 v[148:151], v[128:129], off
	global_load_dwordx4 v[144:147], v[128:129], off offset:256
	global_load_dwordx4 v[140:143], v[130:131], off
	global_load_dwordx4 v[136:139], v[130:131], off offset:256
	global_load_dwordx4 v[132:135], v[200:201], off
	s_nop 0
	global_load_dwordx4 v[128:131], v[200:201], off offset:256
	v_lshl_add_u64 v[198:199], s[74:75], 0, v[198:199]
	v_lshl_add_u64 v[194:195], v[198:199], 0, v[194:195]
	s_lshl_b32 s26, s6, 2
	v_cndmask_b32_e64 v185, 0, 1, s[16:17]
	s_ashr_i32 s27, s26, 31
	v_cmp_ne_u32_e64 s[6:7], 1, v185
	s_andn2_b64 vcc, exec, s[16:17]
	v_add_u32_e32 v244, 0x80, v170
	v_ashrrev_i32_e32 v245, 31, v244
	v_lshlrev_b64 v[244:245], 12, v[244:245]
	v_lshl_add_u64 v[244:245], v[168:169], 0, v[244:245]
	global_load_dwordx4 v[206:209], v[244:245], off
	global_load_dwordx4 v[210:213], v[244:245], off offset:256
	v_add_u32_e32 v244, 0x90, v170
	v_ashrrev_i32_e32 v245, 31, v244
	v_lshlrev_b64 v[244:245], 12, v[244:245]
	v_lshl_add_u64 v[244:245], v[168:169], 0, v[244:245]
	global_load_dwordx4 v[214:217], v[244:245], off
	global_load_dwordx4 v[218:221], v[244:245], off offset:256
	v_add_u32_e32 v244, 0xa0, v170
	v_ashrrev_i32_e32 v245, 31, v244
	v_lshlrev_b64 v[244:245], 12, v[244:245]
	v_lshl_add_u64 v[244:245], v[168:169], 0, v[244:245]
	global_load_dwordx4 v[228:231], v[244:245], off
	global_load_dwordx4 v[232:235], v[244:245], off offset:256
	v_add_u32_e32 v244, 0xb0, v170
	v_ashrrev_i32_e32 v245, 31, v244
	v_lshlrev_b64 v[244:245], 12, v[244:245]
	v_lshl_add_u64 v[244:245], v[168:169], 0, v[244:245]
	global_load_dwordx4 v[236:239], v[244:245], off
	global_load_dwordx4 v[240:243], v[244:245], off offset:256
	s_waitcnt vmcnt(0)
	v_lshlrev_b32_e32 v198, 16, v186
	v_and_b32_e32 v199, 0xffff0000, v186
	v_lshlrev_b32_e32 v186, 16, v187
	v_and_b32_e32 v187, 0xffff0000, v187
	v_lshlrev_b32_e32 v200, 16, v188
	v_and_b32_e32 v201, 0xffff0000, v188
	v_lshlrev_b32_e32 v188, 16, v189
	v_and_b32_e32 v189, 0xffff0000, v189
	v_lshlrev_b32_e32 v202, 16, v190
	v_and_b32_e32 v203, 0xffff0000, v190
	v_lshlrev_b32_e32 v190, 16, v191
	v_and_b32_e32 v191, 0xffff0000, v191
	v_lshlrev_b32_e32 v204, 16, v192
	v_and_b32_e32 v205, 0xffff0000, v192
	v_lshlrev_b32_e32 v192, 16, v193
	v_and_b32_e32 v193, 0xffff0000, v193
	v_pk_add_f32 v[126:127], v[126:127], v[186:187]
	v_pk_add_f32 v[124:125], v[124:125], v[198:199]
	v_pk_add_f32 v[122:123], v[122:123], v[188:189]
	v_pk_add_f32 v[120:121], v[120:121], v[200:201]
	v_pk_add_f32 v[118:119], v[118:119], v[190:191]
	v_pk_add_f32 v[116:117], v[116:117], v[202:203]
	v_pk_add_f32 v[114:115], v[114:115], v[192:193]
	v_pk_add_f32 v[112:113], v[112:113], v[204:205]
	v_cvt_pk_bf16_f32 v186, v124, v125
	v_cvt_pk_bf16_f32 v187, v126, v127
	v_cvt_pk_bf16_f32 v188, v120, v121
	v_cvt_pk_bf16_f32 v189, v122, v123
	v_cvt_pk_bf16_f32 v190, v116, v117
	v_cvt_pk_bf16_f32 v191, v118, v119
	v_cvt_pk_bf16_f32 v192, v112, v113
	v_cvt_pk_bf16_f32 v193, v114, v115
	global_store_dwordx4 v[194:195], v[186:189], off
	global_store_dwordx4 v[194:195], v[190:193], off offset:256
	s_cbranch_vccnz .LBB0_770
	v_mul_f32_e32 v113, v113, v113
	v_mul_f32_e32 v125, v125, v125
	v_mul_f32_e32 v121, v121, v121
	v_mul_f32_e32 v117, v117, v117
	v_fmac_f32_e32 v113, v112, v112
	v_mul_f32_e32 v112, v115, v115
	v_fmac_f32_e32 v125, v124, v124
	v_mul_f32_e32 v124, v127, v127
	v_fmac_f32_e32 v121, v120, v120
	v_mul_f32_e32 v120, v123, v123
	v_fmac_f32_e32 v117, v116, v116
	v_mul_f32_e32 v116, v119, v119
	v_fmac_f32_e32 v112, v114, v114
	v_and_b32_e32 v114, 64, v184
	v_fmac_f32_e32 v124, v126, v126
	v_fmac_f32_e32 v120, v122, v122
	v_fmac_f32_e32 v116, v118, v118
	v_add_f32_e32 v112, v113, v112
	v_xor_b32_e32 v113, 16, v184
	v_add_u32_e32 v114, 64, v114
	v_add_f32_e32 v124, v125, v124
	v_add_f32_e32 v120, v121, v120
	v_add_f32_e32 v116, v117, v116
	v_cmp_lt_i32_e32 vcc, v113, v114
	v_add_f32_e32 v120, v124, v120
	v_add_f32_e32 v112, v116, v112
	v_cndmask_b32_e32 v113, v184, v113, vcc
	v_add_f32_e32 v112, v120, v112
	v_lshlrev_b32_e32 v113, 2, v113
	v_mov_b32_e32 v113, v112
	s_nop 1
	v_permlane16_swap_b32_e32 v113, v112
	v_add_f32_e32 v112, v112, v113
	v_xor_b32_e32 v113, 32, v184
	v_cmp_lt_i32_e32 vcc, v113, v114
	s_nop 1
	v_cndmask_b32_e32 v113, v184, v113, vcc
	v_lshlrev_b32_e32 v113, 2, v113
	v_mov_b32_e32 v113, v112
	s_nop 1
	v_permlane32_swap_b32_e32 v113, v112
	v_add_f32_e32 v112, v112, v113
	s_and_saveexec_b64 s[28:29], s[2:3]
	s_cbranch_execz .LBB0_769
	v_lshlrev_b64 v[114:115], 7, v[170:171]
	v_lshl_add_u64 v[114:115], s[64:65], 0, v[114:115]
	v_lshl_add_u64 v[114:115], s[26:27], 2, v[114:115]
	s_lshl_b32 s8, s42, 2
	v_lshl_add_u64 v[114:115], v[114:115], 0, s[8:9]
	s_waitcnt lgkmcnt(0)
	global_store_dword v[114:115], v112, off

; __device__ __forceinline__ unsigned cvt_pk_bf16(float lo, float hi) { f32x2 v = {lo, hi}; return __builtin_bit_cast(unsigned, __builtin_convertvector(v, bf2_t)); }
;     __device__ __forceinline__ void operator()(const f32x4 (&acc)[2][2][4][2], const Unit& u, int wr, int wc, int fr, int fq) const {
;     ...
;                 for (int bj = 0; bj < 2; ++bj) {
;                     const u32x4 w = raw[m][bj];
;                     const f32x4 r0 = {__uint_as_float(w.x << 16), __uint_as_float(w.x & 0xffff0000u), __uint_as_float(w.y << 16), __uint_as_float(w.y & 0xffff0000u)};
;                     const f32x4 r1 = {__uint_as_float(w.z << 16), __uint_as_float(w.z & 0xffff0000u), __uint_as_float(w.w << 16), __uint_as_float(w.w & 0xffff0000u)};
;                     const f32x4 v0 = r0 + acc[ai][bj][m][0], v1 = r1 + acc[ai][bj][m][1];
;                     if (out32) { *(f32x4*)(out32 + off + bj * HALF) = v0; *(f32x4*)(out32 + off + bj * HALF + 4) = v1; }
;                     if (XB) { u32x4 o; o.x = cvt_pk_bf16(v0[0], v0[1]); o.y = cvt_pk_bf16(v0[2], v0[3]); o.z = cvt_pk_bf16(v1[0], v1[1]); o.w = cvt_pk_bf16(v1[2], v1[3]);
;                               *(u32x4*)(XB + off + bj * HALF) = o;
;                               sq += ((v0[0] * v0[0] + v0[1] * v0[1]) + (v0[2] * v0[2] + v0[3] * v0[3])) + ((v1[0] * v1[0] + v1[1] * v1[1]) + (v1[2] * v1[2] + v1[3] * v1[3])); }
;                 }
;                 if (XB) { sq += __shfl_xor(sq, 16); sq += __shfl_xor(sq, 32); if (fq == 0) SS[(size_t)row * 32 + u.pn * 4 + wc] = sq; }
.LBB0_773:
	v_lshlrev_b32_e32 v106, 16, v144
	v_and_b32_e32 v107, 0xffff0000, v144
	v_lshlrev_b32_e32 v108, 16, v145
	v_and_b32_e32 v109, 0xffff0000, v145
	v_lshlrev_b32_e32 v110, 16, v146
	v_and_b32_e32 v111, 0xffff0000, v146
	v_lshlrev_b32_e32 v114, 16, v147
	v_and_b32_e32 v115, 0xffff0000, v147
	v_pk_add_f32 v[102:103], v[102:103], v[108:109]
	v_pk_add_f32 v[100:101], v[100:101], v[106:107]
	v_pk_add_f32 v[98:99], v[98:99], v[114:115]
	v_pk_add_f32 v[96:97], v[96:97], v[110:111]
	v_cvt_pk_bf16_f32 v106, v100, v101
	v_cvt_pk_bf16_f32 v107, v102, v103
	v_cvt_pk_bf16_f32 v108, v96, v97
	v_cvt_pk_bf16_f32 v109, v98, v99
	s_and_b64 vcc, exec, s[6:7]
	global_store_dwordx4 v[112:113], v[106:109], off offset:256
	s_cbranch_vccnz .LBB0_777
	v_mul_f32_e32 v97, v97, v97
	v_mul_f32_e32 v101, v101, v101
	v_fmac_f32_e32 v97, v96, v96
	v_mul_f32_e32 v96, v99, v99
	v_fmac_f32_e32 v101, v100, v100
	v_mul_f32_e32 v100, v103, v103
	v_fmac_f32_e32 v96, v98, v98
	v_and_b32_e32 v98, 64, v184
	v_fmac_f32_e32 v100, v102, v102
	v_add_f32_e32 v96, v97, v96
	v_xor_b32_e32 v97, 16, v184
	v_add_u32_e32 v98, 64, v98
	v_add_f32_e32 v100, v101, v100
	v_cmp_lt_i32_e32 vcc, v97, v98
	v_add_f32_e32 v96, v100, v96
	v_add_f32_e32 v96, v96, v104
	v_cndmask_b32_e32 v97, v184, v97, vcc
	v_lshlrev_b32_e32 v97, 2, v97
	v_mov_b32_e32 v97, v96
	s_nop 1
	v_permlane16_swap_b32_e32 v97, v96
	v_add_f32_e32 v96, v96, v97
	v_xor_b32_e32 v97, 32, v184
	v_cmp_lt_i32_e32 vcc, v97, v98
	s_nop 1
	v_cndmask_b32_e32 v97, v184, v97, vcc
	v_lshlrev_b32_e32 v97, 2, v97
	v_mov_b32_e32 v97, v96
	s_nop 1
	v_permlane32_swap_b32_e32 v97, v96
	v_add_f32_e32 v96, v96, v97
	s_and_saveexec_b64 s[28:29], s[2:3]
	s_cbranch_execz .LBB0_776
	v_lshlrev_b64 v[98:99], 7, v[176:177]
	v_lshl_add_u64 v[98:99], s[64:65], 0, v[98:99]
	v_lshl_add_u64 v[98:99], s[26:27], 2, v[98:99]
	s_lshl_b32 s8, s42, 2
	v_lshl_add_u64 v[98:99], v[98:99], 0, s[8:9]
	s_waitcnt lgkmcnt(0)
	global_store_dword v[98:99], v96, off

; __device__ __forceinline__ unsigned cvt_pk_bf16(float lo, float hi) { f32x2 v = {lo, hi}; return __builtin_bit_cast(unsigned, __builtin_convertvector(v, bf2_t)); }
;     __device__ __forceinline__ void operator()(const f32x4 (&acc)[2][2][4][2], const Unit& u, int wr, int wc, int fr, int fq) const {
;     ...
;                 for (int bj = 0; bj < 2; ++bj) {
;                     const u32x4 w = raw[m][bj];
;                     const f32x4 r0 = {__uint_as_float(w.x << 16), __uint_as_float(w.x & 0xffff0000u), __uint_as_float(w.y << 16), __uint_as_float(w.y & 0xffff0000u)};
;                     const f32x4 r1 = {__uint_as_float(w.z << 16), __uint_as_float(w.z & 0xffff0000u), __uint_as_float(w.w << 16), __uint_as_float(w.w & 0xffff0000u)};
;                     const f32x4 v0 = r0 + acc[ai][bj][m][0], v1 = r1 + acc[ai][bj][m][1];
;                     if (out32) { *(f32x4*)(out32 + off + bj * HALF) = v0; *(f32x4*)(out32 + off + bj * HALF + 4) = v1; }
;                     if (XB) { u32x4 o; o.x = cvt_pk_bf16(v0[0], v0[1]); o.y = cvt_pk_bf16(v0[2], v0[3]); o.z = cvt_pk_bf16(v1[0], v1[1]); o.w = cvt_pk_bf16(v1[2], v1[3]);
;                               *(u32x4*)(XB + off + bj * HALF) = o;
;                               sq += ((v0[0] * v0[0] + v0[1] * v0[1]) + (v0[2] * v0[2] + v0[3] * v0[3])) + ((v1[0] * v1[0] + v1[1] * v1[1]) + (v1[2] * v1[2] + v1[3] * v1[3])); }
;                 }
;                 if (XB) { sq += __shfl_xor(sq, 16); sq += __shfl_xor(sq, 32); if (fq == 0) SS[(size_t)row * 32 + u.pn * 4 + wc] = sq; }
.LBB0_780:
	v_lshlrev_b32_e32 v90, 16, v136
	v_and_b32_e32 v91, 0xffff0000, v136
	v_lshlrev_b32_e32 v92, 16, v137
	v_and_b32_e32 v93, 0xffff0000, v137
	v_lshlrev_b32_e32 v94, 16, v138
	v_and_b32_e32 v95, 0xffff0000, v138
	v_lshlrev_b32_e32 v98, 16, v139
	v_and_b32_e32 v99, 0xffff0000, v139
	v_pk_add_f32 v[86:87], v[86:87], v[92:93]
	v_pk_add_f32 v[84:85], v[84:85], v[90:91]
	v_pk_add_f32 v[82:83], v[82:83], v[98:99]
	v_pk_add_f32 v[80:81], v[80:81], v[94:95]
	v_cvt_pk_bf16_f32 v90, v84, v85
	v_cvt_pk_bf16_f32 v91, v86, v87
	v_cvt_pk_bf16_f32 v92, v80, v81
	v_cvt_pk_bf16_f32 v93, v82, v83
	s_and_b64 vcc, exec, s[6:7]
	global_store_dwordx4 v[96:97], v[90:93], off offset:256
	s_cbranch_vccnz .LBB0_784
	v_mul_f32_e32 v81, v81, v81
	v_mul_f32_e32 v85, v85, v85
	v_fmac_f32_e32 v81, v80, v80
	v_mul_f32_e32 v80, v83, v83
	v_fmac_f32_e32 v85, v84, v84
	v_mul_f32_e32 v84, v87, v87
	v_fmac_f32_e32 v80, v82, v82
	v_and_b32_e32 v82, 64, v184
	v_fmac_f32_e32 v84, v86, v86
	v_add_f32_e32 v80, v81, v80
	v_xor_b32_e32 v81, 16, v184
	v_add_u32_e32 v82, 64, v82
	v_add_f32_e32 v84, v85, v84
	v_cmp_lt_i32_e32 vcc, v81, v82
	v_add_f32_e32 v80, v84, v80
	v_add_f32_e32 v80, v80, v88
	v_cndmask_b32_e32 v81, v184, v81, vcc
	v_lshlrev_b32_e32 v81, 2, v81
	v_mov_b32_e32 v81, v80
	s_nop 1
	v_permlane16_swap_b32_e32 v81, v80
	v_add_f32_e32 v80, v80, v81
	v_xor_b32_e32 v81, 32, v184
	v_cmp_lt_i32_e32 vcc, v81, v82
	s_nop 1
	v_cndmask_b32_e32 v81, v184, v81, vcc
	v_lshlrev_b32_e32 v81, 2, v81
	v_mov_b32_e32 v81, v80
	s_nop 1
	v_permlane32_swap_b32_e32 v81, v80
	v_add_f32_e32 v80, v80, v81
	s_and_saveexec_b64 s[28:29], s[2:3]
	s_cbranch_execz .LBB0_783
	v_lshlrev_b64 v[82:83], 7, v[174:175]
	v_lshl_add_u64 v[82:83], s[64:65], 0, v[82:83]
	v_lshl_add_u64 v[82:83], s[26:27], 2, v[82:83]
	s_lshl_b32 s8, s42, 2
	v_lshl_add_u64 v[82:83], v[82:83], 0, s[8:9]
	s_waitcnt lgkmcnt(0)
	global_store_dword v[82:83], v80, off

; __device__ __forceinline__ unsigned cvt_pk_bf16(float lo, float hi) { f32x2 v = {lo, hi}; return __builtin_bit_cast(unsigned, __builtin_convertvector(v, bf2_t)); }
;     __device__ __forceinline__ void operator()(const f32x4 (&acc)[2][2][4][2], const Unit& u, int wr, int wc, int fr, int fq) const {
;     ...
;                 for (int bj = 0; bj < 2; ++bj) {
;                     const u32x4 w = raw[m][bj];
;                     const f32x4 r0 = {__uint_as_float(w.x << 16), __uint_as_float(w.x & 0xffff0000u), __uint_as_float(w.y << 16), __uint_as_float(w.y & 0xffff0000u)};
;                     const f32x4 r1 = {__uint_as_float(w.z << 16), __uint_as_float(w.z & 0xffff0000u), __uint_as_float(w.w << 16), __uint_as_float(w.w & 0xffff0000u)};
;                     const f32x4 v0 = r0 + acc[ai][bj][m][0], v1 = r1 + acc[ai][bj][m][1];
;                     if (out32) { *(f32x4*)(out32 + off + bj * HALF) = v0; *(f32x4*)(out32 + off + bj * HALF + 4) = v1; }
;                     if (XB) { u32x4 o; o.x = cvt_pk_bf16(v0[0], v0[1]); o.y = cvt_pk_bf16(v0[2], v0[3]); o.z = cvt_pk_bf16(v1[0], v1[1]); o.w = cvt_pk_bf16(v1[2], v1[3]);
;                               *(u32x4*)(XB + off + bj * HALF) = o;
;                               sq += ((v0[0] * v0[0] + v0[1] * v0[1]) + (v0[2] * v0[2] + v0[3] * v0[3])) + ((v1[0] * v1[0] + v1[1] * v1[1]) + (v1[2] * v1[2] + v1[3] * v1[3])); }
;                 }
;                 if (XB) { sq += __shfl_xor(sq, 16); sq += __shfl_xor(sq, 32); if (fq == 0) SS[(size_t)row * 32 + u.pn * 4 + wc] = sq; }
.LBB0_787:
	v_lshlrev_b32_e32 v74, 16, v128
	v_and_b32_e32 v75, 0xffff0000, v128
	v_lshlrev_b32_e32 v76, 16, v129
	v_and_b32_e32 v77, 0xffff0000, v129
	v_lshlrev_b32_e32 v78, 16, v130
	v_and_b32_e32 v79, 0xffff0000, v130
	v_lshlrev_b32_e32 v82, 16, v131
	v_and_b32_e32 v83, 0xffff0000, v131
	v_pk_add_f32 v[70:71], v[70:71], v[76:77]
	v_pk_add_f32 v[68:69], v[68:69], v[74:75]
	v_pk_add_f32 v[66:67], v[66:67], v[82:83]
	v_pk_add_f32 v[64:65], v[64:65], v[78:79]
	v_cvt_pk_bf16_f32 v74, v68, v69
	v_cvt_pk_bf16_f32 v75, v70, v71
	v_cvt_pk_bf16_f32 v76, v64, v65
	v_cvt_pk_bf16_f32 v77, v66, v67
	s_and_b64 vcc, exec, s[6:7]
	global_store_dwordx4 v[80:81], v[74:77], off offset:256
	s_cbranch_vccnz .LBB0_791
	v_mul_f32_e32 v65, v65, v65
	v_mul_f32_e32 v69, v69, v69
	v_fmac_f32_e32 v65, v64, v64
	v_mul_f32_e32 v64, v67, v67
	v_fmac_f32_e32 v69, v68, v68
	v_mul_f32_e32 v68, v71, v71
	v_fmac_f32_e32 v64, v66, v66
	v_and_b32_e32 v66, 64, v184
	v_fmac_f32_e32 v68, v70, v70
	v_add_f32_e32 v64, v65, v64
	v_xor_b32_e32 v65, 16, v184
	v_add_u32_e32 v66, 64, v66
	v_add_f32_e32 v68, v69, v68
	v_cmp_lt_i32_e32 vcc, v65, v66
	v_add_f32_e32 v64, v68, v64
	v_add_f32_e32 v64, v64, v72
	v_cndmask_b32_e32 v65, v184, v65, vcc
	v_lshlrev_b32_e32 v65, 2, v65
	v_mov_b32_e32 v65, v64
	s_nop 1
	v_permlane16_swap_b32_e32 v65, v64
	v_add_f32_e32 v64, v64, v65
	v_xor_b32_e32 v65, 32, v184
	v_cmp_lt_i32_e32 vcc, v65, v66
	s_nop 1
	v_cndmask_b32_e32 v65, v184, v65, vcc
	v_lshlrev_b32_e32 v65, 2, v65
	v_mov_b32_e32 v65, v64
	s_nop 1
	v_permlane32_swap_b32_e32 v65, v64
	v_add_f32_e32 v64, v64, v65
	s_and_saveexec_b64 s[28:29], s[2:3]
	s_cbranch_execz .LBB0_790
	v_lshlrev_b64 v[66:67], 7, v[172:173]
	v_lshl_add_u64 v[66:67], s[64:65], 0, v[66:67]
	v_lshl_add_u64 v[66:67], s[26:27], 2, v[66:67]
	s_lshl_b32 s8, s42, 2
	v_lshl_add_u64 v[66:67], v[66:67], 0, s[8:9]
	s_waitcnt lgkmcnt(0)
	global_store_dword v[66:67], v64, off

; __device__ __forceinline__ unsigned cvt_pk_bf16(float lo, float hi) { f32x2 v = {lo, hi}; return __builtin_bit_cast(unsigned, __builtin_convertvector(v, bf2_t)); }
;     __device__ __forceinline__ void operator()(const f32x4 (&acc)[2][2][4][2], const Unit& u, int wr, int wc, int fr, int fq) const {
;     ...
;                 for (int bj = 0; bj < 2; ++bj) {
;                     const u32x4 w = raw[m][bj];
;                     const f32x4 r0 = {__uint_as_float(w.x << 16), __uint_as_float(w.x & 0xffff0000u), __uint_as_float(w.y << 16), __uint_as_float(w.y & 0xffff0000u)};
;                     const f32x4 r1 = {__uint_as_float(w.z << 16), __uint_as_float(w.z & 0xffff0000u), __uint_as_float(w.w << 16), __uint_as_float(w.w & 0xffff0000u)};
;                     const f32x4 v0 = r0 + acc[ai][bj][m][0], v1 = r1 + acc[ai][bj][m][1];
;                     if (out32) { *(f32x4*)(out32 + off + bj * HALF) = v0; *(f32x4*)(out32 + off + bj * HALF + 4) = v1; }
;                     if (XB) { u32x4 o; o.x = cvt_pk_bf16(v0[0], v0[1]); o.y = cvt_pk_bf16(v0[2], v0[3]); o.z = cvt_pk_bf16(v1[0], v1[1]); o.w = cvt_pk_bf16(v1[2], v1[3]);
;                               *(u32x4*)(XB + off + bj * HALF) = o;
;                               sq += ((v0[0] * v0[0] + v0[1] * v0[1]) + (v0[2] * v0[2] + v0[3] * v0[3])) + ((v1[0] * v1[0] + v1[1] * v1[1]) + (v1[2] * v1[2] + v1[3] * v1[3])); }
;                 }
;                 if (XB) { sq += __shfl_xor(sq, 16); sq += __shfl_xor(sq, 32); if (fq == 0) SS[(size_t)row * 32 + u.pn * 4 + wc] = sq; }
.LBB0_794:
	v_lshlrev_b32_e32 v58, 16, v88
	v_and_b32_e32 v59, 0xffff0000, v88
	v_lshlrev_b32_e32 v60, 16, v89
	v_and_b32_e32 v61, 0xffff0000, v89
	v_lshlrev_b32_e32 v62, 16, v90
	v_and_b32_e32 v63, 0xffff0000, v90
	v_lshlrev_b32_e32 v88, 16, v91
	v_and_b32_e32 v89, 0xffff0000, v91
	v_pk_add_f32 v[54:55], v[54:55], v[60:61]
	v_pk_add_f32 v[52:53], v[52:53], v[58:59]
	v_pk_add_f32 v[50:51], v[50:51], v[88:89]
	v_pk_add_f32 v[48:49], v[48:49], v[62:63]
	v_cvt_pk_bf16_f32 v58, v52, v53
	v_cvt_pk_bf16_f32 v59, v54, v55
	v_cvt_pk_bf16_f32 v60, v48, v49
	v_cvt_pk_bf16_f32 v61, v50, v51
	s_and_b64 vcc, exec, s[6:7]
	global_store_dwordx4 v[100:101], v[58:61], off offset:256
	s_cbranch_vccnz .LBB0_798
	v_mul_f32_e32 v49, v49, v49
	v_mul_f32_e32 v53, v53, v53
	v_fmac_f32_e32 v49, v48, v48
	v_mul_f32_e32 v48, v51, v51
	v_fmac_f32_e32 v53, v52, v52
	v_mul_f32_e32 v52, v55, v55
	v_fmac_f32_e32 v48, v50, v50
	v_and_b32_e32 v50, 64, v184
	v_fmac_f32_e32 v52, v54, v54
	v_add_f32_e32 v48, v49, v48
	v_xor_b32_e32 v49, 16, v184
	v_add_u32_e32 v50, 64, v50
	v_add_f32_e32 v52, v53, v52
	v_cmp_lt_i32_e32 vcc, v49, v50
	v_add_f32_e32 v48, v52, v48
	v_add_f32_e32 v48, v48, v56
	v_cndmask_b32_e32 v49, v184, v49, vcc
	v_lshlrev_b32_e32 v49, 2, v49
	v_mov_b32_e32 v49, v48
	s_nop 1
	v_permlane16_swap_b32_e32 v49, v48
	v_add_f32_e32 v48, v48, v49
	v_xor_b32_e32 v49, 32, v184
	v_cmp_lt_i32_e32 vcc, v49, v50
	s_nop 1
	v_cndmask_b32_e32 v49, v184, v49, vcc
	v_lshlrev_b32_e32 v49, 2, v49
	v_mov_b32_e32 v49, v48
	s_nop 1
	v_permlane32_swap_b32_e32 v49, v48
	v_add_f32_e32 v48, v48, v49
	s_and_saveexec_b64 s[28:29], s[2:3]
	s_cbranch_execz .LBB0_797
	v_lshlrev_b64 v[50:51], 7, v[98:99]
	v_lshl_add_u64 v[50:51], s[64:65], 0, v[50:51]
	v_lshl_add_u64 v[50:51], s[26:27], 2, v[50:51]
	s_lshl_b32 s8, s42, 2
	v_lshl_add_u64 v[50:51], v[50:51], 0, s[8:9]
	s_waitcnt lgkmcnt(0)
	global_store_dword v[50:51], v48, off

; __device__ __forceinline__ unsigned cvt_pk_bf16(float lo, float hi) { f32x2 v = {lo, hi}; return __builtin_bit_cast(unsigned, __builtin_convertvector(v, bf2_t)); }
;     __device__ __forceinline__ void operator()(const f32x4 (&acc)[2][2][4][2], const Unit& u, int wr, int wc, int fr, int fq) const {
;     ...
;                     const u32x4 w = raw[m][bj];
;                     const f32x4 r0 = {__uint_as_float(w.x << 16), __uint_as_float(w.x & 0xffff0000u), __uint_as_float(w.y << 16), __uint_as_float(w.y & 0xffff0000u)};
;                     const f32x4 r1 = {__uint_as_float(w.z << 16), __uint_as_float(w.z & 0xffff0000u), __uint_as_float(w.w << 16), __uint_as_float(w.w & 0xffff0000u)};
;                     const f32x4 v0 = r0 + acc[ai][bj][m][0], v1 = r1 + acc[ai][bj][m][1];
;                     if (out32) { *(f32x4*)(out32 + off + bj * HALF) = v0; *(f32x4*)(out32 + off + bj * HALF + 4) = v1; }
;                     if (XB) { u32x4 o; o.x = cvt_pk_bf16(v0[0], v0[1]); o.y = cvt_pk_bf16(v0[2], v0[3]); o.z = cvt_pk_bf16(v1[0], v1[1]); o.w = cvt_pk_bf16(v1[2], v1[3]);
;                               *(u32x4*)(XB + off + bj * HALF) = o;
;                               sq += ((v0[0] * v0[0] + v0[1] * v0[1]) + (v0[2] * v0[2] + v0[3] * v0[3])) + ((v1[0] * v1[0] + v1[1] * v1[1]) + (v1[2] * v1[2] + v1[3] * v1[3])); }
;                 }
;                 if (XB) { sq += __shfl_xor(sq, 16); sq += __shfl_xor(sq, 32); if (fq == 0) SS[(size_t)row * 32 + u.pn * 4 + wc] = sq; }
.LBB0_801:
	v_lshlrev_b32_e32 v42, 16, v80
	v_and_b32_e32 v43, 0xffff0000, v80
	v_lshlrev_b32_e32 v44, 16, v81
	v_and_b32_e32 v45, 0xffff0000, v81
	v_lshlrev_b32_e32 v46, 16, v82
	v_and_b32_e32 v47, 0xffff0000, v82
	v_lshlrev_b32_e32 v50, 16, v83
	v_and_b32_e32 v51, 0xffff0000, v83
	v_pk_add_f32 v[38:39], v[38:39], v[44:45]
	v_pk_add_f32 v[36:37], v[36:37], v[42:43]
	v_pk_add_f32 v[34:35], v[34:35], v[50:51]
	v_pk_add_f32 v[32:33], v[32:33], v[46:47]
	v_cvt_pk_bf16_f32 v42, v36, v37
	v_cvt_pk_bf16_f32 v43, v38, v39
	v_cvt_pk_bf16_f32 v44, v32, v33
	v_cvt_pk_bf16_f32 v45, v34, v35
	s_and_b64 vcc, exec, s[6:7]
	global_store_dwordx4 v[48:49], v[42:45], off offset:256
	s_cbranch_vccnz .LBB0_805
	v_mul_f32_e32 v33, v33, v33
	v_mul_f32_e32 v37, v37, v37
	v_fmac_f32_e32 v33, v32, v32
	v_mul_f32_e32 v32, v35, v35
	v_fmac_f32_e32 v37, v36, v36
	v_mul_f32_e32 v36, v39, v39
	v_fmac_f32_e32 v32, v34, v34
	v_and_b32_e32 v34, 64, v184
	v_fmac_f32_e32 v36, v38, v38
	v_add_f32_e32 v32, v33, v32
	v_xor_b32_e32 v33, 16, v184
	v_add_u32_e32 v34, 64, v34
	v_add_f32_e32 v36, v37, v36
	v_cmp_lt_i32_e32 vcc, v33, v34
	v_add_f32_e32 v32, v36, v32
	v_add_f32_e32 v32, v32, v40
	v_cndmask_b32_e32 v33, v184, v33, vcc
	v_lshlrev_b32_e32 v33, 2, v33
	v_mov_b32_e32 v33, v32
	s_nop 1
	v_permlane16_swap_b32_e32 v33, v32
	v_add_f32_e32 v32, v32, v33
	v_xor_b32_e32 v33, 32, v184
	v_cmp_lt_i32_e32 vcc, v33, v34
	s_nop 1
	v_cndmask_b32_e32 v33, v184, v33, vcc
	v_lshlrev_b32_e32 v33, 2, v33
	v_mov_b32_e32 v33, v32
	s_nop 1
	v_permlane32_swap_b32_e32 v33, v32
	v_add_f32_e32 v32, v32, v33
	s_and_saveexec_b64 s[28:29], s[2:3]
	s_cbranch_execz .LBB0_804
	v_lshlrev_b64 v[34:35], 7, v[96:97]
	v_lshl_add_u64 v[34:35], s[64:65], 0, v[34:35]
	v_lshl_add_u64 v[34:35], s[26:27], 2, v[34:35]
	s_lshl_b32 s8, s42, 2
	v_lshl_add_u64 v[34:35], v[34:35], 0, s[8:9]
	s_waitcnt lgkmcnt(0)
	global_store_dword v[34:35], v32, off

; __device__ __forceinline__ unsigned cvt_pk_bf16(float lo, float hi) { f32x2 v = {lo, hi}; return __builtin_bit_cast(unsigned, __builtin_convertvector(v, bf2_t)); }
;     __device__ __forceinline__ void operator()(const f32x4 (&acc)[2][2][4][2], const Unit& u, int wr, int wc, int fr, int fq) const {
;     ...
;                     const u32x4 w = raw[m][bj];
;                     const f32x4 r0 = {__uint_as_float(w.x << 16), __uint_as_float(w.x & 0xffff0000u), __uint_as_float(w.y << 16), __uint_as_float(w.y & 0xffff0000u)};
;                     const f32x4 r1 = {__uint_as_float(w.z << 16), __uint_as_float(w.z & 0xffff0000u), __uint_as_float(w.w << 16), __uint_as_float(w.w & 0xffff0000u)};
;                     const f32x4 v0 = r0 + acc[ai][bj][m][0], v1 = r1 + acc[ai][bj][m][1];
;                     if (out32) { *(f32x4*)(out32 + off + bj * HALF) = v0; *(f32x4*)(out32 + off + bj * HALF + 4) = v1; }
;                     if (XB) { u32x4 o; o.x = cvt_pk_bf16(v0[0], v0[1]); o.y = cvt_pk_bf16(v0[2], v0[3]); o.z = cvt_pk_bf16(v1[0], v1[1]); o.w = cvt_pk_bf16(v1[2], v1[3]);
;                               *(u32x4*)(XB + off + bj * HALF) = o;
;                               sq += ((v0[0] * v0[0] + v0[1] * v0[1]) + (v0[2] * v0[2] + v0[3] * v0[3])) + ((v1[0] * v1[0] + v1[1] * v1[1]) + (v1[2] * v1[2] + v1[3] * v1[3])); }
;                 }
;                 if (XB) { sq += __shfl_xor(sq, 16); sq += __shfl_xor(sq, 32); if (fq == 0) SS[(size_t)row * 32 + u.pn * 4 + wc] = sq; }
.LBB0_808:
	v_lshlrev_b32_e32 v26, 16, v72
	v_and_b32_e32 v27, 0xffff0000, v72
	v_lshlrev_b32_e32 v28, 16, v73
	v_and_b32_e32 v29, 0xffff0000, v73
	v_lshlrev_b32_e32 v30, 16, v74
	v_and_b32_e32 v31, 0xffff0000, v74
	v_lshlrev_b32_e32 v34, 16, v75
	v_and_b32_e32 v35, 0xffff0000, v75
	v_pk_add_f32 v[22:23], v[22:23], v[28:29]
	v_pk_add_f32 v[20:21], v[20:21], v[26:27]
	v_pk_add_f32 v[18:19], v[18:19], v[34:35]
	v_pk_add_f32 v[16:17], v[16:17], v[30:31]
	v_cvt_pk_bf16_f32 v26, v20, v21
	v_cvt_pk_bf16_f32 v27, v22, v23
	v_cvt_pk_bf16_f32 v28, v16, v17
	v_cvt_pk_bf16_f32 v29, v18, v19
	s_and_b64 vcc, exec, s[6:7]
	global_store_dwordx4 v[32:33], v[26:29], off offset:256
	s_cbranch_vccnz .LBB0_812
	v_mul_f32_e32 v17, v17, v17
	v_mul_f32_e32 v21, v21, v21
	v_fmac_f32_e32 v17, v16, v16
	v_mul_f32_e32 v16, v19, v19
	v_fmac_f32_e32 v21, v20, v20
	v_mul_f32_e32 v20, v23, v23
	v_fmac_f32_e32 v16, v18, v18
	v_and_b32_e32 v18, 64, v184
	v_fmac_f32_e32 v20, v22, v22
	v_add_f32_e32 v16, v17, v16
	v_xor_b32_e32 v17, 16, v184
	v_add_u32_e32 v18, 64, v18
	v_add_f32_e32 v20, v21, v20
	v_cmp_lt_i32_e32 vcc, v17, v18
	v_add_f32_e32 v16, v20, v16
	v_add_f32_e32 v16, v16, v24
	v_cndmask_b32_e32 v17, v184, v17, vcc
	v_lshlrev_b32_e32 v17, 2, v17
	v_mov_b32_e32 v17, v16
	s_nop 1
	v_permlane16_swap_b32_e32 v17, v16
	v_add_f32_e32 v16, v16, v17
	v_xor_b32_e32 v17, 32, v184
	v_cmp_lt_i32_e32 vcc, v17, v18
	s_nop 1
	v_cndmask_b32_e32 v17, v184, v17, vcc
	v_lshlrev_b32_e32 v17, 2, v17
	v_mov_b32_e32 v17, v16
	s_nop 1
	v_permlane32_swap_b32_e32 v17, v16
	v_add_f32_e32 v16, v16, v17
	s_and_saveexec_b64 s[28:29], s[2:3]
	s_cbranch_execz .LBB0_811
	v_lshlrev_b64 v[18:19], 7, v[94:95]
	v_lshl_add_u64 v[18:19], s[64:65], 0, v[18:19]
	v_lshl_add_u64 v[18:19], s[26:27], 2, v[18:19]
	s_lshl_b32 s8, s42, 2
	v_lshl_add_u64 v[18:19], v[18:19], 0, s[8:9]
	s_waitcnt lgkmcnt(0)
	global_store_dword v[18:19], v16, off

;     __device__ __forceinline__ void operator()(const f32x4 (&acc)[2][2][4][2], const Unit& u, int wr, int wc, int fr, int fq) const {
;     ...
;                 for (int bj = 0; bj < 2; ++bj) {
;                     const f32x4 a = acc[ai][bj][m][0], b = acc[ai][bj][m][1];
;                     float sq = ((a[0] * a[0] + a[1] * a[1]) + (a[2] * a[2] + a[3] * a[3])) + ((b[0] * b[0] + b[1] * b[1]) + (b[2] * b[2] + b[3] * b[3]));
;                     sq += __shfl_xor(sq, 16); sq += __shfl_xor(sq, 32);
;                     if (fq == 0) xl[((ai * HALF + wr * 64 + m * 16 + fr) * 2 + bj) * 4 + wc] = sq;
;                 }
.LBB0_972:
	s_or_b64 exec, exec, s[0:1]
	v_mul_f32_e32 v130, v113, v113
	s_waitcnt lgkmcnt(0)
	v_mul_f32_e32 v131, v115, v115
	v_fmac_f32_e32 v130, v112, v112
	v_fmac_f32_e32 v131, v114, v114
	v_add_f32_e32 v130, v130, v131
	v_mul_f32_e32 v131, v105, v105
	v_mul_f32_e32 v132, v107, v107
	v_fmac_f32_e32 v131, v104, v104
	v_fmac_f32_e32 v132, v106, v106
	v_add_f32_e32 v131, v131, v132
	v_add_f32_e32 v130, v130, v131
	v_mov_b32_e32 v131, v130
	s_nop 1
	v_permlane16_swap_b32_e32 v131, v130
	v_add_f32_e32 v130, v130, v131
	v_mov_b32_e32 v131, v130
	s_nop 1
	v_permlane32_swap_b32_e32 v131, v130
	v_add_f32_e32 v130, v130, v131
	s_and_saveexec_b64 s[0:1], s[2:3]
	s_cbranch_execz .LBB0_974
	s_waitcnt lgkmcnt(0)
	ds_write_b32 v200, v130 offset:16
.LBB0_974:
	s_or_b64 exec, exec, s[0:1]
	v_mul_f32_e32 v130, v117, v117
	s_waitcnt lgkmcnt(0)
	v_mul_f32_e32 v131, v119, v119
	v_fmac_f32_e32 v130, v116, v116
	v_fmac_f32_e32 v131, v118, v118
	v_add_f32_e32 v130, v130, v131
	v_mul_f32_e32 v131, v109, v109
	v_mul_f32_e32 v132, v111, v111
	v_fmac_f32_e32 v131, v108, v108
	v_fmac_f32_e32 v132, v110, v110
	v_add_f32_e32 v131, v131, v132
	v_add_f32_e32 v130, v130, v131
	v_mov_b32_e32 v131, v130
	s_nop 1
	v_permlane16_swap_b32_e32 v131, v130
	v_add_f32_e32 v130, v130, v131
	v_mov_b32_e32 v131, v130
	s_nop 1
	v_permlane32_swap_b32_e32 v131, v130
	v_add_f32_e32 v130, v130, v131
	s_and_saveexec_b64 s[0:1], s[2:3]
	s_cbranch_execz .LBB0_976
	s_waitcnt lgkmcnt(0)
	ds_write_b32 v201, v130
.LBB0_976:
	s_or_b64 exec, exec, s[0:1]
	v_mul_f32_e32 v130, v97, v97
	s_waitcnt lgkmcnt(0)
	v_mul_f32_e32 v131, v99, v99
	v_fmac_f32_e32 v130, v96, v96
	v_fmac_f32_e32 v131, v98, v98
	v_add_f32_e32 v130, v130, v131
	v_mul_f32_e32 v131, v89, v89
	v_mul_f32_e32 v132, v91, v91
	v_fmac_f32_e32 v131, v88, v88
	v_fmac_f32_e32 v132, v90, v90
	v_add_f32_e32 v131, v131, v132
	v_add_f32_e32 v130, v130, v131
	v_mov_b32_e32 v131, v130
	s_nop 1
	v_permlane16_swap_b32_e32 v131, v130
	v_add_f32_e32 v130, v130, v131
	v_mov_b32_e32 v131, v130
	s_nop 1
	v_permlane32_swap_b32_e32 v131, v130
	v_add_f32_e32 v130, v130, v131
	s_and_saveexec_b64 s[0:1], s[2:3]
	s_cbranch_execz .LBB0_978
	s_waitcnt lgkmcnt(0)
	ds_write_b32 v201, v130 offset:16
.LBB0_978:
	s_or_b64 exec, exec, s[0:1]
	v_mul_f32_e32 v130, v101, v101
	s_waitcnt lgkmcnt(0)
	v_mul_f32_e32 v131, v103, v103
	v_fmac_f32_e32 v130, v100, v100
	v_fmac_f32_e32 v131, v102, v102
	v_add_f32_e32 v130, v130, v131
	v_mul_f32_e32 v131, v93, v93
	v_mul_f32_e32 v132, v95, v95
	v_fmac_f32_e32 v131, v92, v92
	v_fmac_f32_e32 v132, v94, v94
	v_add_f32_e32 v131, v131, v132
	v_add_f32_e32 v130, v130, v131
	v_mov_b32_e32 v131, v130
	s_nop 1
	v_permlane16_swap_b32_e32 v131, v130
	v_add_f32_e32 v130, v130, v131
	v_mov_b32_e32 v131, v130
	s_nop 1
	v_permlane32_swap_b32_e32 v131, v130
	v_add_f32_e32 v130, v130, v131
	s_and_saveexec_b64 s[0:1], s[2:3]
	s_cbranch_execz .LBB0_980
	s_waitcnt lgkmcnt(0)
	ds_write_b32 v202, v130
.LBB0_980:
	s_or_b64 exec, exec, s[0:1]
	v_mul_f32_e32 v130, v81, v81
	s_waitcnt lgkmcnt(0)
	v_mul_f32_e32 v131, v83, v83
	v_fmac_f32_e32 v130, v80, v80
	v_fmac_f32_e32 v131, v82, v82
	v_add_f32_e32 v130, v130, v131
	v_mul_f32_e32 v131, v73, v73
	v_mul_f32_e32 v132, v75, v75
	v_fmac_f32_e32 v131, v72, v72
	v_fmac_f32_e32 v132, v74, v74
	v_add_f32_e32 v131, v131, v132
	v_add_f32_e32 v130, v130, v131
	v_mov_b32_e32 v131, v130
	s_nop 1
	v_permlane16_swap_b32_e32 v131, v130
	v_add_f32_e32 v130, v130, v131
	v_mov_b32_e32 v131, v130
	s_nop 1
	v_permlane32_swap_b32_e32 v131, v130
	v_add_f32_e32 v130, v130, v131
	s_and_saveexec_b64 s[0:1], s[2:3]
	s_cbranch_execz .LBB0_982
	s_waitcnt lgkmcnt(0)
	ds_write_b32 v202, v130 offset:16
.LBB0_982:
	s_or_b64 exec, exec, s[0:1]
	v_mul_f32_e32 v130, v85, v85
	s_waitcnt lgkmcnt(0)
	v_mul_f32_e32 v131, v87, v87
	v_fmac_f32_e32 v130, v84, v84
	v_fmac_f32_e32 v131, v86, v86
	v_add_f32_e32 v130, v130, v131
	v_mul_f32_e32 v131, v77, v77
	v_mul_f32_e32 v132, v79, v79
	v_fmac_f32_e32 v131, v76, v76
	v_fmac_f32_e32 v132, v78, v78
	v_add_f32_e32 v131, v131, v132
	v_add_f32_e32 v130, v130, v131
	v_mov_b32_e32 v131, v130
	s_nop 1
	v_permlane16_swap_b32_e32 v131, v130
	v_add_f32_e32 v130, v130, v131
	v_mov_b32_e32 v131, v130
	s_nop 1
	v_permlane32_swap_b32_e32 v131, v130
	v_add_f32_e32 v130, v130, v131
	s_and_saveexec_b64 s[0:1], s[2:3]
	s_cbranch_execz .LBB0_984
	s_waitcnt lgkmcnt(0)
	ds_write_b32 v203, v130
.LBB0_984:
	s_or_b64 exec, exec, s[0:1]
	v_mul_f32_e32 v130, v69, v69
	s_waitcnt lgkmcnt(0)
	v_mul_f32_e32 v131, v71, v71
	v_fmac_f32_e32 v130, v68, v68
	v_fmac_f32_e32 v131, v70, v70
	v_add_f32_e32 v130, v130, v131
	v_mul_f32_e32 v131, v65, v65
	v_mul_f32_e32 v132, v67, v67
	v_fmac_f32_e32 v131, v64, v64
	v_fmac_f32_e32 v132, v66, v66
	v_add_f32_e32 v131, v131, v132
	v_add_f32_e32 v130, v130, v131
	v_mov_b32_e32 v131, v130
	s_nop 1
	v_permlane16_swap_b32_e32 v131, v130
	v_add_f32_e32 v130, v130, v131
	v_mov_b32_e32 v131, v130
	s_nop 1
	v_permlane32_swap_b32_e32 v131, v130
	v_add_f32_e32 v130, v130, v131
	s_and_saveexec_b64 s[0:1], s[2:3]
	s_cbranch_execz .LBB0_986
	s_waitcnt lgkmcnt(0)
	ds_write_b32 v203, v130 offset:16
;     __device__ __forceinline__ void operator()(const f32x4 (&acc)[2][2][4][2], const Unit& u, int wr, int wc, int fr, int fq) const {
;     ...
;                 for (int bj = 0; bj < 2; ++bj) {
;                     const f32x4 a = acc[ai][bj][m][0], b = acc[ai][bj][m][1];
;                     float sq = ((a[0] * a[0] + a[1] * a[1]) + (a[2] * a[2] + a[3] * a[3])) + ((b[0] * b[0] + b[1] * b[1]) + (b[2] * b[2] + b[3] * b[3]));
;                     sq += __shfl_xor(sq, 16); sq += __shfl_xor(sq, 32);
;                     if (fq == 0) xl[((ai * HALF + wr * 64 + m * 16 + fr) * 2 + bj) * 4 + wc] = sq;
;                 }
.LBB0_986:
	s_or_b64 exec, exec, s[0:1]
	v_mul_f32_e32 v130, v61, v61
	s_waitcnt lgkmcnt(0)
	v_mul_f32_e32 v131, v63, v63
	v_fmac_f32_e32 v130, v60, v60
	v_fmac_f32_e32 v131, v62, v62
	v_add_f32_e32 v130, v130, v131
	v_mul_f32_e32 v131, v57, v57
	v_mul_f32_e32 v132, v59, v59
	v_fmac_f32_e32 v131, v56, v56
	v_fmac_f32_e32 v132, v58, v58
	v_add_f32_e32 v131, v131, v132
	v_add_f32_e32 v130, v130, v131
	v_mov_b32_e32 v131, v130
	s_nop 1
	v_permlane16_swap_b32_e32 v131, v130
	v_add_f32_e32 v130, v130, v131
	v_mov_b32_e32 v131, v130
	s_nop 1
	v_permlane32_swap_b32_e32 v131, v130
	v_add_f32_e32 v130, v130, v131
	s_and_saveexec_b64 s[0:1], s[2:3]
	s_cbranch_execz .LBB0_988
	s_waitcnt lgkmcnt(0)
	ds_write_b32 v204, v130
.LBB0_988:
	s_or_b64 exec, exec, s[0:1]
	v_mul_f32_e32 v130, v49, v49
	s_waitcnt lgkmcnt(0)
	v_mul_f32_e32 v131, v51, v51
	v_fmac_f32_e32 v130, v48, v48
	v_fmac_f32_e32 v131, v50, v50
	v_add_f32_e32 v130, v130, v131
	v_mul_f32_e32 v131, v41, v41
	v_mul_f32_e32 v132, v43, v43
	v_fmac_f32_e32 v131, v40, v40
	v_fmac_f32_e32 v132, v42, v42
	v_add_f32_e32 v131, v131, v132
	v_add_f32_e32 v130, v130, v131
	v_mov_b32_e32 v131, v130
	s_nop 1
	v_permlane16_swap_b32_e32 v131, v130
	v_add_f32_e32 v130, v130, v131
	v_mov_b32_e32 v131, v130
	s_nop 1
	v_permlane32_swap_b32_e32 v131, v130
	v_add_f32_e32 v130, v130, v131
	s_and_saveexec_b64 s[0:1], s[2:3]
	s_cbranch_execz .LBB0_990
	s_waitcnt lgkmcnt(0)
	ds_write_b32 v204, v130 offset:16
.LBB0_990:
	s_or_b64 exec, exec, s[0:1]
	v_mul_f32_e32 v130, v53, v53
	s_waitcnt lgkmcnt(0)
	v_mul_f32_e32 v131, v55, v55
	v_fmac_f32_e32 v130, v52, v52
	v_fmac_f32_e32 v131, v54, v54
	v_add_f32_e32 v130, v130, v131
	v_mul_f32_e32 v131, v45, v45
	v_mul_f32_e32 v132, v47, v47
	v_fmac_f32_e32 v131, v44, v44
	v_fmac_f32_e32 v132, v46, v46
	v_add_f32_e32 v131, v131, v132
	v_add_f32_e32 v130, v130, v131
	v_mov_b32_e32 v131, v130
	s_nop 1
	v_permlane16_swap_b32_e32 v131, v130
	v_add_f32_e32 v130, v130, v131
	v_mov_b32_e32 v131, v130
	s_nop 1
	v_permlane32_swap_b32_e32 v131, v130
	v_add_f32_e32 v130, v130, v131
	s_and_saveexec_b64 s[0:1], s[2:3]
	s_cbranch_execz .LBB0_992
	s_waitcnt lgkmcnt(0)
	ds_write_b32 v205, v130
.LBB0_992:
	s_or_b64 exec, exec, s[0:1]
	v_mul_f32_e32 v130, v33, v33
	s_waitcnt lgkmcnt(0)
	v_mul_f32_e32 v131, v35, v35
	v_fmac_f32_e32 v130, v32, v32
	v_fmac_f32_e32 v131, v34, v34
	v_add_f32_e32 v130, v130, v131
	v_mul_f32_e32 v131, v25, v25
	v_mul_f32_e32 v132, v27, v27
	v_fmac_f32_e32 v131, v24, v24
	v_fmac_f32_e32 v132, v26, v26
	v_add_f32_e32 v131, v131, v132
	v_add_f32_e32 v130, v130, v131
	v_mov_b32_e32 v131, v130
	s_nop 1
	v_permlane16_swap_b32_e32 v131, v130
	v_add_f32_e32 v130, v130, v131
	v_mov_b32_e32 v131, v130
	s_nop 1
	v_permlane32_swap_b32_e32 v131, v130
	v_add_f32_e32 v130, v130, v131
	s_and_saveexec_b64 s[0:1], s[2:3]
	s_cbranch_execz .LBB0_994
	s_waitcnt lgkmcnt(0)
	ds_write_b32 v205, v130 offset:16
.LBB0_994:
	s_or_b64 exec, exec, s[0:1]
	v_mul_f32_e32 v130, v37, v37
	s_waitcnt lgkmcnt(0)
	v_mul_f32_e32 v131, v39, v39
	v_fmac_f32_e32 v130, v36, v36
	v_fmac_f32_e32 v131, v38, v38
	v_add_f32_e32 v130, v130, v131
	v_mul_f32_e32 v131, v29, v29
	v_mul_f32_e32 v132, v31, v31
	v_fmac_f32_e32 v131, v28, v28
	v_fmac_f32_e32 v132, v30, v30
	v_add_f32_e32 v131, v131, v132
	v_add_f32_e32 v130, v130, v131
	v_mov_b32_e32 v131, v130
	s_nop 1
	v_permlane16_swap_b32_e32 v131, v130
	v_add_f32_e32 v130, v130, v131
	v_mov_b32_e32 v131, v130
	s_nop 1
	v_permlane32_swap_b32_e32 v131, v130
	v_add_f32_e32 v130, v130, v131
	s_and_saveexec_b64 s[0:1], s[2:3]
	s_cbranch_execz .LBB0_996
	s_waitcnt lgkmcnt(0)
	ds_write_b32 v206, v130
.LBB0_996:
	s_or_b64 exec, exec, s[0:1]
	v_mul_f32_e32 v130, v17, v17
	s_waitcnt lgkmcnt(0)
	v_mul_f32_e32 v131, v19, v19
	v_fmac_f32_e32 v130, v16, v16
	v_fmac_f32_e32 v131, v18, v18
	v_add_f32_e32 v130, v130, v131
	v_mul_f32_e32 v131, v9, v9
	v_mul_f32_e32 v132, v11, v11
	v_fmac_f32_e32 v131, v8, v8
	v_fmac_f32_e32 v132, v10, v10
	v_add_f32_e32 v131, v131, v132
	v_add_f32_e32 v130, v130, v131
	v_mov_b32_e32 v131, v130
	s_nop 1
	v_permlane16_swap_b32_e32 v131, v130
	v_add_f32_e32 v130, v130, v131
	v_mov_b32_e32 v131, v130
	s_nop 1
	v_permlane32_swap_b32_e32 v131, v130
	v_add_f32_e32 v130, v130, v131
	s_and_saveexec_b64 s[0:1], s[2:3]
	s_cbranch_execz .LBB0_998
	s_waitcnt lgkmcnt(0)
	ds_write_b32 v206, v130 offset:16
.LBB0_998:
	s_or_b64 exec, exec, s[0:1]
	v_mul_f32_e32 v130, v21, v21
	s_waitcnt lgkmcnt(0)
	v_mul_f32_e32 v131, v23, v23
	v_fmac_f32_e32 v130, v20, v20
	v_fmac_f32_e32 v131, v22, v22
	v_add_f32_e32 v130, v130, v131
	v_mul_f32_e32 v131, v13, v13
	v_mul_f32_e32 v132, v15, v15
	v_fmac_f32_e32 v131, v12, v12
	v_fmac_f32_e32 v132, v14, v14
	v_add_f32_e32 v131, v131, v132
	v_add_f32_e32 v130, v130, v131
	v_mov_b32_e32 v131, v130
	s_nop 1
	v_permlane16_swap_b32_e32 v131, v130
	v_add_f32_e32 v130, v130, v131
	v_mov_b32_e32 v131, v130
	s_nop 1
	v_permlane32_swap_b32_e32 v131, v130
	v_add_f32_e32 v130, v130, v131
	s_and_saveexec_b64 s[0:1], s[2:3]
	s_cbranch_execz .LBB0_1000
	s_waitcnt lgkmcnt(0)
	ds_write_b32 v207, v130

; __device__ __forceinline__ unsigned cvt_pk_bf16(float lo, float hi) { f32x2 v = {lo, hi}; return __builtin_bit_cast(unsigned, __builtin_convertvector(v, bf2_t)); }
;     __device__ __forceinline__ void operator()(const f32x4 (&acc)[2][2][4][2], const Unit& u, int wr, int wc, int fr, int fq) const {
;     ...
;             u32x4 raw[4][2];
; #pragma unroll
;             for (int m = 0; m < 4; ++m)
; #pragma unroll
;                 for (int bj = 0; bj < 2; ++bj) raw[m][bj] = *(const u32x4*)(base16 + (size_t)(row0 + ai * HALF + m * 16) * 2048 + col0 + bj * HALF);
; #pragma unroll
;             for (int m = 0; m < 4; ++m) {
;                 const int row = row0 + ai * HALF + m * 16;
;                 const size_t off = (size_t)row * 2048 + col0;
;                 float sq = 0.f;
; #pragma unroll
;                 for (int bj = 0; bj < 2; ++bj) {
;                     const u32x4 w = raw[m][bj];
;                     const f32x4 r0 = {__uint_as_float(w.x << 16), __uint_as_float(w.x & 0xffff0000u), __uint_as_float(w.y << 16), __uint_as_float(w.y & 0xffff0000u)};
;                     const f32x4 r1 = {__uint_as_float(w.z << 16), __uint_as_float(w.z & 0xffff0000u), __uint_as_float(w.w << 16), __uint_as_float(w.w & 0xffff0000u)};
;                     const f32x4 v0 = r0 + acc[ai][bj][m][0], v1 = r1 + acc[ai][bj][m][1];
;                     if (out32) { *(f32x4*)(out32 + off + bj * HALF) = v0; *(f32x4*)(out32 + off + bj * HALF + 4) = v1; }
;                     if (XB) { u32x4 o; o.x = cvt_pk_bf16(v0[0], v0[1]); o.y = cvt_pk_bf16(v0[2], v0[3]); o.z = cvt_pk_bf16(v1[0], v1[1]); o.w = cvt_pk_bf16(v1[2], v1[3]);
;                               *(u32x4*)(XB + off + bj * HALF) = o;
;                               sq += ((v0[0] * v0[0] + v0[1] * v0[1]) + (v0[2] * v0[2] + v0[3] * v0[3])) + ((v1[0] * v1[0] + v1[1] * v1[1]) + (v1[2] * v1[2] + v1[3] * v1[3])); }
;                 }
;                 if (XB) { sq += __shfl_xor(sq, 16); sq += __shfl_xor(sq, 32); if (fq == 0) SS[(size_t)row * 32 + u.pn * 4 + wc] = sq; }
.LBB0_1183:
	v_lshl_or_b32 v128, s6, 8, v180
	v_lshl_add_u32 v170, s8, 8, v178
	v_ashrrev_i32_e32 v129, 31, v128
	v_lshlrev_b64 v[194:195], 1, v[128:129]
	v_ashrrev_i32_e32 v171, 31, v170
	v_lshl_add_u64 v[168:169], s[74:75], 0, v[194:195]
	v_lshlrev_b64 v[198:199], 12, v[170:171]
	v_or_b32_e32 v176, 16, v170
	v_or_b32_e32 v174, 32, v170
	v_lshl_add_u64 v[128:129], v[168:169], 0, v[198:199]
	v_or_b32_e32 v172, 48, v170
	v_ashrrev_i32_e32 v177, 31, v176
	v_ashrrev_i32_e32 v175, 31, v174
	global_load_dwordx4 v[186:189], v[128:129], off
	global_load_dwordx4 v[190:193], v[128:129], off offset:256
	v_ashrrev_i32_e32 v173, 31, v172
	v_lshlrev_b64 v[128:129], 12, v[176:177]
	v_lshlrev_b64 v[130:131], 12, v[174:175]
	v_lshlrev_b64 v[132:133], 12, v[172:173]
	v_lshl_add_u64 v[128:129], v[168:169], 0, v[128:129]
	v_lshl_add_u64 v[130:131], v[168:169], 0, v[130:131]
	v_lshl_add_u64 v[200:201], v[168:169], 0, v[132:133]
	global_load_dwordx4 v[148:151], v[128:129], off
	global_load_dwordx4 v[144:147], v[128:129], off offset:256
	global_load_dwordx4 v[140:143], v[130:131], off
	global_load_dwordx4 v[136:139], v[130:131], off offset:256
	global_load_dwordx4 v[132:135], v[200:201], off
	s_nop 0
	global_load_dwordx4 v[128:131], v[200:201], off offset:256
	v_lshl_add_u64 v[198:199], s[74:75], 0, v[198:199]
	v_lshl_add_u64 v[194:195], v[198:199], 0, v[194:195]
	s_lshl_b32 s26, s6, 2
	v_cndmask_b32_e64 v185, 0, 1, s[16:17]
	s_ashr_i32 s27, s26, 31
	v_cmp_ne_u32_e64 s[6:7], 1, v185
	s_andn2_b64 vcc, exec, s[16:17]
	v_add_u32_e32 v244, 0x80, v170
	v_ashrrev_i32_e32 v245, 31, v244
	v_lshlrev_b64 v[244:245], 12, v[244:245]
	v_lshl_add_u64 v[244:245], v[168:169], 0, v[244:245]
	global_load_dwordx4 v[206:209], v[244:245], off
	global_load_dwordx4 v[210:213], v[244:245], off offset:256
	v_add_u32_e32 v244, 0x90, v170
	v_ashrrev_i32_e32 v245, 31, v244
	v_lshlrev_b64 v[244:245], 12, v[244:245]
	v_lshl_add_u64 v[244:245], v[168:169], 0, v[244:245]
	global_load_dwordx4 v[214:217], v[244:245], off
	global_load_dwordx4 v[218:221], v[244:245], off offset:256
	v_add_u32_e32 v244, 0xa0, v170
	v_ashrrev_i32_e32 v245, 31, v244
	v_lshlrev_b64 v[244:245], 12, v[244:245]
	v_lshl_add_u64 v[244:245], v[168:169], 0, v[244:245]
	global_load_dwordx4 v[228:231], v[244:245], off
	global_load_dwordx4 v[232:235], v[244:245], off offset:256
	v_add_u32_e32 v244, 0xb0, v170
	v_ashrrev_i32_e32 v245, 31, v244
	v_lshlrev_b64 v[244:245], 12, v[244:245]
	v_lshl_add_u64 v[244:245], v[168:169], 0, v[244:245]
	global_load_dwordx4 v[236:239], v[244:245], off
	global_load_dwordx4 v[240:243], v[244:245], off offset:256
	s_waitcnt vmcnt(0)
	v_lshlrev_b32_e32 v198, 16, v186
	v_and_b32_e32 v199, 0xffff0000, v186
	v_lshlrev_b32_e32 v186, 16, v187
	v_and_b32_e32 v187, 0xffff0000, v187
	v_lshlrev_b32_e32 v200, 16, v188
	v_and_b32_e32 v201, 0xffff0000, v188
	v_lshlrev_b32_e32 v188, 16, v189
	v_and_b32_e32 v189, 0xffff0000, v189
	v_lshlrev_b32_e32 v202, 16, v190
	v_and_b32_e32 v203, 0xffff0000, v190
	v_lshlrev_b32_e32 v190, 16, v191
	v_and_b32_e32 v191, 0xffff0000, v191
	v_lshlrev_b32_e32 v204, 16, v192
	v_and_b32_e32 v205, 0xffff0000, v192
	v_lshlrev_b32_e32 v192, 16, v193
	v_and_b32_e32 v193, 0xffff0000, v193
	v_pk_add_f32 v[126:127], v[126:127], v[186:187]
	v_pk_add_f32 v[124:125], v[124:125], v[198:199]
	v_pk_add_f32 v[122:123], v[122:123], v[188:189]
	v_pk_add_f32 v[120:121], v[120:121], v[200:201]
	v_pk_add_f32 v[118:119], v[118:119], v[190:191]
	v_pk_add_f32 v[116:117], v[116:117], v[202:203]
	v_pk_add_f32 v[114:115], v[114:115], v[192:193]
	v_pk_add_f32 v[112:113], v[112:113], v[204:205]
	v_cvt_pk_bf16_f32 v186, v124, v125
	v_cvt_pk_bf16_f32 v187, v126, v127
	v_cvt_pk_bf16_f32 v188, v120, v121
	v_cvt_pk_bf16_f32 v189, v122, v123
	v_cvt_pk_bf16_f32 v190, v116, v117
	v_cvt_pk_bf16_f32 v191, v118, v119
	v_cvt_pk_bf16_f32 v192, v112, v113
	v_cvt_pk_bf16_f32 v193, v114, v115
	global_store_dwordx4 v[194:195], v[186:189], off
	global_store_dwordx4 v[194:195], v[190:193], off offset:256
	s_cbranch_vccnz .LBB0_1187
	v_mul_f32_e32 v113, v113, v113
	v_mul_f32_e32 v125, v125, v125
	v_mul_f32_e32 v121, v121, v121
	v_mul_f32_e32 v117, v117, v117
	v_fmac_f32_e32 v113, v112, v112
	v_mul_f32_e32 v112, v115, v115
	v_fmac_f32_e32 v125, v124, v124
	v_mul_f32_e32 v124, v127, v127
	v_fmac_f32_e32 v121, v120, v120
	v_mul_f32_e32 v120, v123, v123
	v_fmac_f32_e32 v117, v116, v116
	v_mul_f32_e32 v116, v119, v119
	v_fmac_f32_e32 v112, v114, v114
	v_and_b32_e32 v114, 64, v184
	v_fmac_f32_e32 v124, v126, v126
	v_fmac_f32_e32 v120, v122, v122
	v_fmac_f32_e32 v116, v118, v118
	v_add_f32_e32 v112, v113, v112
	v_xor_b32_e32 v113, 16, v184
	v_add_u32_e32 v114, 64, v114
	v_add_f32_e32 v124, v125, v124
	v_add_f32_e32 v120, v121, v120
	v_add_f32_e32 v116, v117, v116
	v_cmp_lt_i32_e32 vcc, v113, v114
	v_add_f32_e32 v120, v124, v120
	v_add_f32_e32 v112, v116, v112
	v_cndmask_b32_e32 v113, v184, v113, vcc
	v_add_f32_e32 v112, v120, v112
	v_lshlrev_b32_e32 v113, 2, v113
	v_mov_b32_e32 v113, v112
	s_nop 1
	v_permlane16_swap_b32_e32 v113, v112
	v_add_f32_e32 v112, v112, v113
	v_xor_b32_e32 v113, 32, v184
	v_cmp_lt_i32_e32 vcc, v113, v114
	s_nop 1
	v_cndmask_b32_e32 v113, v184, v113, vcc
	v_lshlrev_b32_e32 v113, 2, v113
	v_mov_b32_e32 v113, v112
	s_nop 1
	v_permlane32_swap_b32_e32 v113, v112
	v_add_f32_e32 v112, v112, v113
	s_and_saveexec_b64 s[28:29], s[2:3]
	s_cbranch_execz .LBB0_1186
	v_lshlrev_b64 v[114:115], 7, v[170:171]
	v_lshl_add_u64 v[114:115], s[64:65], 0, v[114:115]
	v_lshl_add_u64 v[114:115], s[26:27], 2, v[114:115]
	s_lshl_b32 s8, s38, 2
	v_lshl_add_u64 v[114:115], v[114:115], 0, s[8:9]
	s_waitcnt lgkmcnt(0)
	global_store_dword v[114:115], v112, off

; __device__ __forceinline__ unsigned cvt_pk_bf16(float lo, float hi) { f32x2 v = {lo, hi}; return __builtin_bit_cast(unsigned, __builtin_convertvector(v, bf2_t)); }
;     __device__ __forceinline__ void operator()(const f32x4 (&acc)[2][2][4][2], const Unit& u, int wr, int wc, int fr, int fq) const {
;     ...
;                     const u32x4 w = raw[m][bj];
;                     const f32x4 r0 = {__uint_as_float(w.x << 16), __uint_as_float(w.x & 0xffff0000u), __uint_as_float(w.y << 16), __uint_as_float(w.y & 0xffff0000u)};
;                     const f32x4 r1 = {__uint_as_float(w.z << 16), __uint_as_float(w.z & 0xffff0000u), __uint_as_float(w.w << 16), __uint_as_float(w.w & 0xffff0000u)};
;                     const f32x4 v0 = r0 + acc[ai][bj][m][0], v1 = r1 + acc[ai][bj][m][1];
;                     if (out32) { *(f32x4*)(out32 + off + bj * HALF) = v0; *(f32x4*)(out32 + off + bj * HALF + 4) = v1; }
;                     if (XB) { u32x4 o; o.x = cvt_pk_bf16(v0[0], v0[1]); o.y = cvt_pk_bf16(v0[2], v0[3]); o.z = cvt_pk_bf16(v1[0], v1[1]); o.w = cvt_pk_bf16(v1[2], v1[3]);
;                               *(u32x4*)(XB + off + bj * HALF) = o;
;                               sq += ((v0[0] * v0[0] + v0[1] * v0[1]) + (v0[2] * v0[2] + v0[3] * v0[3])) + ((v1[0] * v1[0] + v1[1] * v1[1]) + (v1[2] * v1[2] + v1[3] * v1[3])); }
;                 }
;                 if (XB) { sq += __shfl_xor(sq, 16); sq += __shfl_xor(sq, 32); if (fq == 0) SS[(size_t)row * 32 + u.pn * 4 + wc] = sq; }
.LBB0_1190:
	v_readlane_b32 s48, v254, 24
	v_readlane_b32 s49, v254, 25
	v_readlane_b32 s50, v254, 26
	v_readlane_b32 s51, v254, 27
	v_readlane_b32 s52, v254, 28
	v_readlane_b32 s53, v254, 29
	v_lshlrev_b32_e32 v106, 16, v144
	v_and_b32_e32 v107, 0xffff0000, v144
	v_lshlrev_b32_e32 v108, 16, v145
	v_and_b32_e32 v109, 0xffff0000, v145
	v_lshlrev_b32_e32 v110, 16, v146
	v_and_b32_e32 v111, 0xffff0000, v146
	v_lshlrev_b32_e32 v114, 16, v147
	v_and_b32_e32 v115, 0xffff0000, v147
	v_readlane_b32 s54, v254, 30
	v_readlane_b32 s55, v254, 31
	s_mov_b64 s[48:49], s[52:53]
	v_pk_add_f32 v[102:103], v[102:103], v[108:109]
	v_pk_add_f32 v[100:101], v[100:101], v[106:107]
	v_pk_add_f32 v[98:99], v[98:99], v[114:115]
	v_pk_add_f32 v[96:97], v[96:97], v[110:111]
	s_mov_b64 s[50:51], s[54:55]
	v_cvt_pk_bf16_f32 v106, v100, v101
	v_cvt_pk_bf16_f32 v107, v102, v103
	v_cvt_pk_bf16_f32 v108, v96, v97
	v_cvt_pk_bf16_f32 v109, v98, v99
	s_and_b64 vcc, exec, s[6:7]
	global_store_dwordx4 v[112:113], v[106:109], off offset:256
	s_cbranch_vccnz .LBB0_1194
	v_mul_f32_e32 v97, v97, v97
	v_mul_f32_e32 v101, v101, v101
	v_fmac_f32_e32 v97, v96, v96
	v_mul_f32_e32 v96, v99, v99
	v_fmac_f32_e32 v101, v100, v100
	v_mul_f32_e32 v100, v103, v103
	v_fmac_f32_e32 v96, v98, v98
	v_and_b32_e32 v98, 64, v184
	v_fmac_f32_e32 v100, v102, v102
	v_add_f32_e32 v96, v97, v96
	v_xor_b32_e32 v97, 16, v184
	v_add_u32_e32 v98, 64, v98
	v_add_f32_e32 v100, v101, v100
	v_cmp_lt_i32_e32 vcc, v97, v98
	v_add_f32_e32 v96, v100, v96
	v_add_f32_e32 v96, v96, v104
	v_cndmask_b32_e32 v97, v184, v97, vcc
	v_lshlrev_b32_e32 v97, 2, v97
	v_mov_b32_e32 v97, v96
	s_nop 1
	v_permlane16_swap_b32_e32 v97, v96
	v_add_f32_e32 v96, v96, v97
	v_xor_b32_e32 v97, 32, v184
	v_cmp_lt_i32_e32 vcc, v97, v98
	s_nop 1
	v_cndmask_b32_e32 v97, v184, v97, vcc
	v_lshlrev_b32_e32 v97, 2, v97
	v_mov_b32_e32 v97, v96
	s_nop 1
	v_permlane32_swap_b32_e32 v97, v96
	v_add_f32_e32 v96, v96, v97
	s_and_saveexec_b64 s[28:29], s[2:3]
	s_cbranch_execz .LBB0_1193
	v_lshlrev_b64 v[98:99], 7, v[176:177]
	v_lshl_add_u64 v[98:99], s[64:65], 0, v[98:99]
	v_lshl_add_u64 v[98:99], s[26:27], 2, v[98:99]
	s_lshl_b32 s8, s38, 2
	v_lshl_add_u64 v[98:99], v[98:99], 0, s[8:9]
	s_waitcnt lgkmcnt(0)
	global_store_dword v[98:99], v96, off

; __device__ __forceinline__ unsigned cvt_pk_bf16(float lo, float hi) { f32x2 v = {lo, hi}; return __builtin_bit_cast(unsigned, __builtin_convertvector(v, bf2_t)); }
;     __device__ __forceinline__ void operator()(const f32x4 (&acc)[2][2][4][2], const Unit& u, int wr, int wc, int fr, int fq) const {
;     ...
;                     const u32x4 w = raw[m][bj];
;                     const f32x4 r0 = {__uint_as_float(w.x << 16), __uint_as_float(w.x & 0xffff0000u), __uint_as_float(w.y << 16), __uint_as_float(w.y & 0xffff0000u)};
;                     const f32x4 r1 = {__uint_as_float(w.z << 16), __uint_as_float(w.z & 0xffff0000u), __uint_as_float(w.w << 16), __uint_as_float(w.w & 0xffff0000u)};
;                     const f32x4 v0 = r0 + acc[ai][bj][m][0], v1 = r1 + acc[ai][bj][m][1];
;                     if (out32) { *(f32x4*)(out32 + off + bj * HALF) = v0; *(f32x4*)(out32 + off + bj * HALF + 4) = v1; }
;                     if (XB) { u32x4 o; o.x = cvt_pk_bf16(v0[0], v0[1]); o.y = cvt_pk_bf16(v0[2], v0[3]); o.z = cvt_pk_bf16(v1[0], v1[1]); o.w = cvt_pk_bf16(v1[2], v1[3]);
;                               *(u32x4*)(XB + off + bj * HALF) = o;
;                               sq += ((v0[0] * v0[0] + v0[1] * v0[1]) + (v0[2] * v0[2] + v0[3] * v0[3])) + ((v1[0] * v1[0] + v1[1] * v1[1]) + (v1[2] * v1[2] + v1[3] * v1[3])); }
;                 }
;                 if (XB) { sq += __shfl_xor(sq, 16); sq += __shfl_xor(sq, 32); if (fq == 0) SS[(size_t)row * 32 + u.pn * 4 + wc] = sq; }
.LBB0_1197:
	v_lshlrev_b32_e32 v90, 16, v136
	v_and_b32_e32 v91, 0xffff0000, v136
	v_lshlrev_b32_e32 v92, 16, v137
	v_and_b32_e32 v93, 0xffff0000, v137
	v_lshlrev_b32_e32 v94, 16, v138
	v_and_b32_e32 v95, 0xffff0000, v138
	v_lshlrev_b32_e32 v98, 16, v139
	v_and_b32_e32 v99, 0xffff0000, v139
	v_pk_add_f32 v[86:87], v[86:87], v[92:93]
	v_pk_add_f32 v[84:85], v[84:85], v[90:91]
	v_pk_add_f32 v[82:83], v[82:83], v[98:99]
	v_pk_add_f32 v[80:81], v[80:81], v[94:95]
	v_cvt_pk_bf16_f32 v90, v84, v85
	v_cvt_pk_bf16_f32 v91, v86, v87
	v_cvt_pk_bf16_f32 v92, v80, v81
	v_cvt_pk_bf16_f32 v93, v82, v83
	s_and_b64 vcc, exec, s[6:7]
	global_store_dwordx4 v[96:97], v[90:93], off offset:256
	s_cbranch_vccnz .LBB0_1201
	v_mul_f32_e32 v81, v81, v81
	v_mul_f32_e32 v85, v85, v85
	v_fmac_f32_e32 v81, v80, v80
	v_mul_f32_e32 v80, v83, v83
	v_fmac_f32_e32 v85, v84, v84
	v_mul_f32_e32 v84, v87, v87
	v_fmac_f32_e32 v80, v82, v82
	v_and_b32_e32 v82, 64, v184
	v_fmac_f32_e32 v84, v86, v86
	v_add_f32_e32 v80, v81, v80
	v_xor_b32_e32 v81, 16, v184
	v_add_u32_e32 v82, 64, v82
	v_add_f32_e32 v84, v85, v84
	v_cmp_lt_i32_e32 vcc, v81, v82
	v_add_f32_e32 v80, v84, v80
	v_add_f32_e32 v80, v80, v88
	v_cndmask_b32_e32 v81, v184, v81, vcc
	v_lshlrev_b32_e32 v81, 2, v81
	v_mov_b32_e32 v81, v80
	s_nop 1
	v_permlane16_swap_b32_e32 v81, v80
	v_add_f32_e32 v80, v80, v81
	v_xor_b32_e32 v81, 32, v184
	v_cmp_lt_i32_e32 vcc, v81, v82
	s_nop 1
	v_cndmask_b32_e32 v81, v184, v81, vcc
	v_lshlrev_b32_e32 v81, 2, v81
	v_mov_b32_e32 v81, v80
	s_nop 1
	v_permlane32_swap_b32_e32 v81, v80
	v_add_f32_e32 v80, v80, v81
	s_and_saveexec_b64 s[28:29], s[2:3]
	s_cbranch_execz .LBB0_1200
	v_lshlrev_b64 v[82:83], 7, v[174:175]
	v_lshl_add_u64 v[82:83], s[64:65], 0, v[82:83]
	v_lshl_add_u64 v[82:83], s[26:27], 2, v[82:83]
	s_lshl_b32 s8, s38, 2
	v_lshl_add_u64 v[82:83], v[82:83], 0, s[8:9]
	s_waitcnt lgkmcnt(0)
	global_store_dword v[82:83], v80, off

; __device__ __forceinline__ unsigned cvt_pk_bf16(float lo, float hi) { f32x2 v = {lo, hi}; return __builtin_bit_cast(unsigned, __builtin_convertvector(v, bf2_t)); }
;     __device__ __forceinline__ void operator()(const f32x4 (&acc)[2][2][4][2], const Unit& u, int wr, int wc, int fr, int fq) const {
;     ...
;                     const u32x4 w = raw[m][bj];
;                     const f32x4 r0 = {__uint_as_float(w.x << 16), __uint_as_float(w.x & 0xffff0000u), __uint_as_float(w.y << 16), __uint_as_float(w.y & 0xffff0000u)};
;                     const f32x4 r1 = {__uint_as_float(w.z << 16), __uint_as_float(w.z & 0xffff0000u), __uint_as_float(w.w << 16), __uint_as_float(w.w & 0xffff0000u)};
;                     const f32x4 v0 = r0 + acc[ai][bj][m][0], v1 = r1 + acc[ai][bj][m][1];
;                     if (out32) { *(f32x4*)(out32 + off + bj * HALF) = v0; *(f32x4*)(out32 + off + bj * HALF + 4) = v1; }
;                     if (XB) { u32x4 o; o.x = cvt_pk_bf16(v0[0], v0[1]); o.y = cvt_pk_bf16(v0[2], v0[3]); o.z = cvt_pk_bf16(v1[0], v1[1]); o.w = cvt_pk_bf16(v1[2], v1[3]);
;                               *(u32x4*)(XB + off + bj * HALF) = o;
;                               sq += ((v0[0] * v0[0] + v0[1] * v0[1]) + (v0[2] * v0[2] + v0[3] * v0[3])) + ((v1[0] * v1[0] + v1[1] * v1[1]) + (v1[2] * v1[2] + v1[3] * v1[3])); }
;                 }
;                 if (XB) { sq += __shfl_xor(sq, 16); sq += __shfl_xor(sq, 32); if (fq == 0) SS[(size_t)row * 32 + u.pn * 4 + wc] = sq; }
.LBB0_1204:
	v_lshlrev_b32_e32 v74, 16, v128
	v_and_b32_e32 v75, 0xffff0000, v128
	v_lshlrev_b32_e32 v76, 16, v129
	v_and_b32_e32 v77, 0xffff0000, v129
	v_lshlrev_b32_e32 v78, 16, v130
	v_and_b32_e32 v79, 0xffff0000, v130
	v_lshlrev_b32_e32 v82, 16, v131
	v_and_b32_e32 v83, 0xffff0000, v131
	v_pk_add_f32 v[70:71], v[70:71], v[76:77]
	v_pk_add_f32 v[68:69], v[68:69], v[74:75]
	v_pk_add_f32 v[66:67], v[66:67], v[82:83]
	v_pk_add_f32 v[64:65], v[64:65], v[78:79]
	v_cvt_pk_bf16_f32 v74, v68, v69
	v_cvt_pk_bf16_f32 v75, v70, v71
	v_cvt_pk_bf16_f32 v76, v64, v65
	v_cvt_pk_bf16_f32 v77, v66, v67
	s_and_b64 vcc, exec, s[6:7]
	global_store_dwordx4 v[80:81], v[74:77], off offset:256
	s_cbranch_vccnz .LBB0_1208
	v_mul_f32_e32 v65, v65, v65
	v_mul_f32_e32 v69, v69, v69
	v_fmac_f32_e32 v65, v64, v64
	v_mul_f32_e32 v64, v67, v67
	v_fmac_f32_e32 v69, v68, v68
	v_mul_f32_e32 v68, v71, v71
	v_fmac_f32_e32 v64, v66, v66
	v_and_b32_e32 v66, 64, v184
	v_fmac_f32_e32 v68, v70, v70
	v_add_f32_e32 v64, v65, v64
	v_xor_b32_e32 v65, 16, v184
	v_add_u32_e32 v66, 64, v66
	v_add_f32_e32 v68, v69, v68
	v_cmp_lt_i32_e32 vcc, v65, v66
	v_add_f32_e32 v64, v68, v64
	v_add_f32_e32 v64, v64, v72
	v_cndmask_b32_e32 v65, v184, v65, vcc
	v_lshlrev_b32_e32 v65, 2, v65
	v_mov_b32_e32 v65, v64
	s_nop 1
	v_permlane16_swap_b32_e32 v65, v64
	v_add_f32_e32 v64, v64, v65
	v_xor_b32_e32 v65, 32, v184
	v_cmp_lt_i32_e32 vcc, v65, v66
	s_nop 1
	v_cndmask_b32_e32 v65, v184, v65, vcc
	v_lshlrev_b32_e32 v65, 2, v65
	v_mov_b32_e32 v65, v64
	s_nop 1
	v_permlane32_swap_b32_e32 v65, v64
	v_add_f32_e32 v64, v64, v65
	s_and_saveexec_b64 s[28:29], s[2:3]
	s_cbranch_execz .LBB0_1207
	v_lshlrev_b64 v[66:67], 7, v[172:173]
	v_lshl_add_u64 v[66:67], s[64:65], 0, v[66:67]
	v_lshl_add_u64 v[66:67], s[26:27], 2, v[66:67]
	s_lshl_b32 s8, s38, 2
	v_lshl_add_u64 v[66:67], v[66:67], 0, s[8:9]
	s_waitcnt lgkmcnt(0)
	global_store_dword v[66:67], v64, off

; __device__ __forceinline__ unsigned cvt_pk_bf16(float lo, float hi) { f32x2 v = {lo, hi}; return __builtin_bit_cast(unsigned, __builtin_convertvector(v, bf2_t)); }
;     __device__ __forceinline__ void operator()(const f32x4 (&acc)[2][2][4][2], const Unit& u, int wr, int wc, int fr, int fq) const {
;     ...
;                     const u32x4 w = raw[m][bj];
;                     const f32x4 r0 = {__uint_as_float(w.x << 16), __uint_as_float(w.x & 0xffff0000u), __uint_as_float(w.y << 16), __uint_as_float(w.y & 0xffff0000u)};
;                     const f32x4 r1 = {__uint_as_float(w.z << 16), __uint_as_float(w.z & 0xffff0000u), __uint_as_float(w.w << 16), __uint_as_float(w.w & 0xffff0000u)};
;                     const f32x4 v0 = r0 + acc[ai][bj][m][0], v1 = r1 + acc[ai][bj][m][1];
;                     if (out32) { *(f32x4*)(out32 + off + bj * HALF) = v0; *(f32x4*)(out32 + off + bj * HALF + 4) = v1; }
;                     if (XB) { u32x4 o; o.x = cvt_pk_bf16(v0[0], v0[1]); o.y = cvt_pk_bf16(v0[2], v0[3]); o.z = cvt_pk_bf16(v1[0], v1[1]); o.w = cvt_pk_bf16(v1[2], v1[3]);
;                               *(u32x4*)(XB + off + bj * HALF) = o;
;                               sq += ((v0[0] * v0[0] + v0[1] * v0[1]) + (v0[2] * v0[2] + v0[3] * v0[3])) + ((v1[0] * v1[0] + v1[1] * v1[1]) + (v1[2] * v1[2] + v1[3] * v1[3])); }
;                 }
;                 if (XB) { sq += __shfl_xor(sq, 16); sq += __shfl_xor(sq, 32); if (fq == 0) SS[(size_t)row * 32 + u.pn * 4 + wc] = sq; }
.LBB0_1211:
	v_lshlrev_b32_e32 v58, 16, v88
	v_and_b32_e32 v59, 0xffff0000, v88
	v_lshlrev_b32_e32 v60, 16, v89
	v_and_b32_e32 v61, 0xffff0000, v89
	v_lshlrev_b32_e32 v62, 16, v90
	v_and_b32_e32 v63, 0xffff0000, v90
	v_lshlrev_b32_e32 v88, 16, v91
	v_and_b32_e32 v89, 0xffff0000, v91
	v_pk_add_f32 v[54:55], v[54:55], v[60:61]
	v_pk_add_f32 v[52:53], v[52:53], v[58:59]
	v_pk_add_f32 v[50:51], v[50:51], v[88:89]
	v_pk_add_f32 v[48:49], v[48:49], v[62:63]
	v_cvt_pk_bf16_f32 v58, v52, v53
	v_cvt_pk_bf16_f32 v59, v54, v55
	v_cvt_pk_bf16_f32 v60, v48, v49
	v_cvt_pk_bf16_f32 v61, v50, v51
	s_and_b64 vcc, exec, s[6:7]
	global_store_dwordx4 v[100:101], v[58:61], off offset:256
	s_cbranch_vccnz .LBB0_1215
	v_mul_f32_e32 v49, v49, v49
	v_mul_f32_e32 v53, v53, v53
	v_fmac_f32_e32 v49, v48, v48
	v_mul_f32_e32 v48, v51, v51
	v_fmac_f32_e32 v53, v52, v52
	v_mul_f32_e32 v52, v55, v55
	v_fmac_f32_e32 v48, v50, v50
	v_and_b32_e32 v50, 64, v184
	v_fmac_f32_e32 v52, v54, v54
	v_add_f32_e32 v48, v49, v48
	v_xor_b32_e32 v49, 16, v184
	v_add_u32_e32 v50, 64, v50
	v_add_f32_e32 v52, v53, v52
	v_cmp_lt_i32_e32 vcc, v49, v50
	v_add_f32_e32 v48, v52, v48
	v_add_f32_e32 v48, v48, v56
	v_cndmask_b32_e32 v49, v184, v49, vcc
	v_lshlrev_b32_e32 v49, 2, v49
	v_mov_b32_e32 v49, v48
	s_nop 1
	v_permlane16_swap_b32_e32 v49, v48
	v_add_f32_e32 v48, v48, v49
	v_xor_b32_e32 v49, 32, v184
	v_cmp_lt_i32_e32 vcc, v49, v50
	s_nop 1
	v_cndmask_b32_e32 v49, v184, v49, vcc
	v_lshlrev_b32_e32 v49, 2, v49
	v_mov_b32_e32 v49, v48
	s_nop 1
	v_permlane32_swap_b32_e32 v49, v48
	v_add_f32_e32 v48, v48, v49
	s_and_saveexec_b64 s[28:29], s[2:3]
	s_cbranch_execz .LBB0_1214
	v_lshlrev_b64 v[50:51], 7, v[98:99]
	v_lshl_add_u64 v[50:51], s[64:65], 0, v[50:51]
	v_lshl_add_u64 v[50:51], s[26:27], 2, v[50:51]
	s_lshl_b32 s8, s38, 2
	v_lshl_add_u64 v[50:51], v[50:51], 0, s[8:9]
	s_waitcnt lgkmcnt(0)
	global_store_dword v[50:51], v48, off

; __device__ __forceinline__ unsigned cvt_pk_bf16(float lo, float hi) { f32x2 v = {lo, hi}; return __builtin_bit_cast(unsigned, __builtin_convertvector(v, bf2_t)); }
;     __device__ __forceinline__ void operator()(const f32x4 (&acc)[2][2][4][2], const Unit& u, int wr, int wc, int fr, int fq) const {
;     ...
;                     const u32x4 w = raw[m][bj];
;                     const f32x4 r0 = {__uint_as_float(w.x << 16), __uint_as_float(w.x & 0xffff0000u), __uint_as_float(w.y << 16), __uint_as_float(w.y & 0xffff0000u)};
;                     const f32x4 r1 = {__uint_as_float(w.z << 16), __uint_as_float(w.z & 0xffff0000u), __uint_as_float(w.w << 16), __uint_as_float(w.w & 0xffff0000u)};
;                     const f32x4 v0 = r0 + acc[ai][bj][m][0], v1 = r1 + acc[ai][bj][m][1];
;                     if (out32) { *(f32x4*)(out32 + off + bj * HALF) = v0; *(f32x4*)(out32 + off + bj * HALF + 4) = v1; }
;                     if (XB) { u32x4 o; o.x = cvt_pk_bf16(v0[0], v0[1]); o.y = cvt_pk_bf16(v0[2], v0[3]); o.z = cvt_pk_bf16(v1[0], v1[1]); o.w = cvt_pk_bf16(v1[2], v1[3]);
;                               *(u32x4*)(XB + off + bj * HALF) = o;
;                               sq += ((v0[0] * v0[0] + v0[1] * v0[1]) + (v0[2] * v0[2] + v0[3] * v0[3])) + ((v1[0] * v1[0] + v1[1] * v1[1]) + (v1[2] * v1[2] + v1[3] * v1[3])); }
;                 }
;                 if (XB) { sq += __shfl_xor(sq, 16); sq += __shfl_xor(sq, 32); if (fq == 0) SS[(size_t)row * 32 + u.pn * 4 + wc] = sq; }
.LBB0_1218:
	v_lshlrev_b32_e32 v42, 16, v80
	v_and_b32_e32 v43, 0xffff0000, v80
	v_lshlrev_b32_e32 v44, 16, v81
	v_and_b32_e32 v45, 0xffff0000, v81
	v_lshlrev_b32_e32 v46, 16, v82
	v_and_b32_e32 v47, 0xffff0000, v82
	v_lshlrev_b32_e32 v50, 16, v83
	v_and_b32_e32 v51, 0xffff0000, v83
	v_pk_add_f32 v[38:39], v[38:39], v[44:45]
	v_pk_add_f32 v[36:37], v[36:37], v[42:43]
	v_pk_add_f32 v[34:35], v[34:35], v[50:51]
	v_pk_add_f32 v[32:33], v[32:33], v[46:47]
	v_cvt_pk_bf16_f32 v42, v36, v37
	v_cvt_pk_bf16_f32 v43, v38, v39
	v_cvt_pk_bf16_f32 v44, v32, v33
	v_cvt_pk_bf16_f32 v45, v34, v35
	s_and_b64 vcc, exec, s[6:7]
	global_store_dwordx4 v[48:49], v[42:45], off offset:256
	s_cbranch_vccnz .LBB0_1222
	v_mul_f32_e32 v33, v33, v33
	v_mul_f32_e32 v37, v37, v37
	v_fmac_f32_e32 v33, v32, v32
	v_mul_f32_e32 v32, v35, v35
	v_fmac_f32_e32 v37, v36, v36
	v_mul_f32_e32 v36, v39, v39
	v_fmac_f32_e32 v32, v34, v34
	v_and_b32_e32 v34, 64, v184
	v_fmac_f32_e32 v36, v38, v38
	v_add_f32_e32 v32, v33, v32
	v_xor_b32_e32 v33, 16, v184
	v_add_u32_e32 v34, 64, v34
	v_add_f32_e32 v36, v37, v36
	v_cmp_lt_i32_e32 vcc, v33, v34
	v_add_f32_e32 v32, v36, v32
	v_add_f32_e32 v32, v32, v40
	v_cndmask_b32_e32 v33, v184, v33, vcc
	v_lshlrev_b32_e32 v33, 2, v33
	v_mov_b32_e32 v33, v32
	s_nop 1
	v_permlane16_swap_b32_e32 v33, v32
	v_add_f32_e32 v32, v32, v33
	v_xor_b32_e32 v33, 32, v184
	v_cmp_lt_i32_e32 vcc, v33, v34
	s_nop 1
	v_cndmask_b32_e32 v33, v184, v33, vcc
	v_lshlrev_b32_e32 v33, 2, v33
	v_mov_b32_e32 v33, v32
	s_nop 1
	v_permlane32_swap_b32_e32 v33, v32
	v_add_f32_e32 v32, v32, v33
	s_and_saveexec_b64 s[28:29], s[2:3]
	s_cbranch_execz .LBB0_1221
	v_lshlrev_b64 v[34:35], 7, v[96:97]
	v_lshl_add_u64 v[34:35], s[64:65], 0, v[34:35]
	v_lshl_add_u64 v[34:35], s[26:27], 2, v[34:35]
	s_lshl_b32 s8, s38, 2
	v_lshl_add_u64 v[34:35], v[34:35], 0, s[8:9]
	s_waitcnt lgkmcnt(0)
	global_store_dword v[34:35], v32, off

; __device__ __forceinline__ unsigned cvt_pk_bf16(float lo, float hi) { f32x2 v = {lo, hi}; return __builtin_bit_cast(unsigned, __builtin_convertvector(v, bf2_t)); }
;     __device__ __forceinline__ void operator()(const f32x4 (&acc)[2][2][4][2], const Unit& u, int wr, int wc, int fr, int fq) const {
;     ...
;                     const u32x4 w = raw[m][bj];
;                     const f32x4 r0 = {__uint_as_float(w.x << 16), __uint_as_float(w.x & 0xffff0000u), __uint_as_float(w.y << 16), __uint_as_float(w.y & 0xffff0000u)};
;                     const f32x4 r1 = {__uint_as_float(w.z << 16), __uint_as_float(w.z & 0xffff0000u), __uint_as_float(w.w << 16), __uint_as_float(w.w & 0xffff0000u)};
;                     const f32x4 v0 = r0 + acc[ai][bj][m][0], v1 = r1 + acc[ai][bj][m][1];
;                     if (out32) { *(f32x4*)(out32 + off + bj * HALF) = v0; *(f32x4*)(out32 + off + bj * HALF + 4) = v1; }
;                     if (XB) { u32x4 o; o.x = cvt_pk_bf16(v0[0], v0[1]); o.y = cvt_pk_bf16(v0[2], v0[3]); o.z = cvt_pk_bf16(v1[0], v1[1]); o.w = cvt_pk_bf16(v1[2], v1[3]);
;                               *(u32x4*)(XB + off + bj * HALF) = o;
;                               sq += ((v0[0] * v0[0] + v0[1] * v0[1]) + (v0[2] * v0[2] + v0[3] * v0[3])) + ((v1[0] * v1[0] + v1[1] * v1[1]) + (v1[2] * v1[2] + v1[3] * v1[3])); }
;                 }
;                 if (XB) { sq += __shfl_xor(sq, 16); sq += __shfl_xor(sq, 32); if (fq == 0) SS[(size_t)row * 32 + u.pn * 4 + wc] = sq; }
.LBB0_1225:
	v_lshlrev_b32_e32 v26, 16, v72
	v_and_b32_e32 v27, 0xffff0000, v72
	v_lshlrev_b32_e32 v28, 16, v73
	v_and_b32_e32 v29, 0xffff0000, v73
	v_lshlrev_b32_e32 v30, 16, v74
	v_and_b32_e32 v31, 0xffff0000, v74
	v_lshlrev_b32_e32 v34, 16, v75
	v_and_b32_e32 v35, 0xffff0000, v75
	v_pk_add_f32 v[22:23], v[22:23], v[28:29]
	v_pk_add_f32 v[20:21], v[20:21], v[26:27]
	v_pk_add_f32 v[18:19], v[18:19], v[34:35]
	v_pk_add_f32 v[16:17], v[16:17], v[30:31]
	v_cvt_pk_bf16_f32 v26, v20, v21
	v_cvt_pk_bf16_f32 v27, v22, v23
	v_cvt_pk_bf16_f32 v28, v16, v17
	v_cvt_pk_bf16_f32 v29, v18, v19
	s_and_b64 vcc, exec, s[6:7]
	global_store_dwordx4 v[32:33], v[26:29], off offset:256
	s_cbranch_vccnz .LBB0_1229
	v_mul_f32_e32 v17, v17, v17
	v_mul_f32_e32 v21, v21, v21
	v_fmac_f32_e32 v17, v16, v16
	v_mul_f32_e32 v16, v19, v19
	v_fmac_f32_e32 v21, v20, v20
	v_mul_f32_e32 v20, v23, v23
	v_fmac_f32_e32 v16, v18, v18
	v_and_b32_e32 v18, 64, v184
	v_fmac_f32_e32 v20, v22, v22
	v_add_f32_e32 v16, v17, v16
	v_xor_b32_e32 v17, 16, v184
	v_add_u32_e32 v18, 64, v18
	v_add_f32_e32 v20, v21, v20
	v_cmp_lt_i32_e32 vcc, v17, v18
	v_add_f32_e32 v16, v20, v16
	v_add_f32_e32 v16, v16, v24
	v_cndmask_b32_e32 v17, v184, v17, vcc
	v_lshlrev_b32_e32 v17, 2, v17
	v_mov_b32_e32 v17, v16
	s_nop 1
	v_permlane16_swap_b32_e32 v17, v16
	v_add_f32_e32 v16, v16, v17
	v_xor_b32_e32 v17, 32, v184
	v_cmp_lt_i32_e32 vcc, v17, v18
	s_nop 1
	v_cndmask_b32_e32 v17, v184, v17, vcc
	v_lshlrev_b32_e32 v17, 2, v17
	v_mov_b32_e32 v17, v16
	s_nop 1
	v_permlane32_swap_b32_e32 v17, v16
	v_add_f32_e32 v16, v16, v17
	s_and_saveexec_b64 s[28:29], s[2:3]
	s_cbranch_execz .LBB0_1228
	v_lshlrev_b64 v[18:19], 7, v[94:95]
	v_lshl_add_u64 v[18:19], s[64:65], 0, v[18:19]
	v_lshl_add_u64 v[18:19], s[26:27], 2, v[18:19]
	s_lshl_b32 s8, s38, 2
	v_lshl_add_u64 v[18:19], v[18:19], 0, s[8:9]
	s_waitcnt lgkmcnt(0)
	global_store_dword v[18:19], v16, off
